# P9/P12 residual epilogues regenerated: 16-byte x loads and y stores via v_permlane16_swap row exchange (same math, same bytes)
# speedup vs baseline: 1.0858x; 1.0118x over previous
.LBB0_1198:
	s_ashr_i32 s25, s24, 31
	s_lshl_b64 s[24:25], s[24:25], 18
	v_lshl_or_b32 v132, s22, 8, v171
	v_lshl_add_u64 v[130:131], s[24:25], 0, v[148:149]
	v_ashrrev_i32_e32 v133, 31, v132
	v_lshl_add_u64 v[130:131], v[130:131], 0, v[132:133]
	v_lshlrev_b64 v[154:155], 1, v[130:131]
	v_lshl_add_u64 v[156:157], s[6:7], 0, v[154:155]
	s_lshl_b64 s[24:25], s[26:27], 2
	s_nop 0
	s_add_u32 s24, s44, s24
	s_nop 0
	s_addc_u32 s25, s45, s25
	v_lshl_add_u64 v[130:131], v[132:133], 2, s[24:25]
	global_load_dwordx4 v[142:145], v[130:131], off
	global_load_dwordx4 v[138:141], v[130:131], off offset:64
	global_load_dwordx4 v[134:137], v[130:131], off offset:512
	s_nop 0
	global_load_dwordx4 v[130:133], v[130:131], off offset:576
	v_lshl_add_u64 v[154:155], s[12:13], 0, v[154:155]
	s_mov_b32 s15, 0x40000
	s_mov_b32 s17, 0x48000
	s_mov_b32 s22, 0x50000
	s_mov_b32 s24, 0x58000
	s_mov_b64 s[28:29], s[20:21]
	s_mov_b64 s[26:27], s[18:19]
	v_and_b32_e32 v168, 16, v224
	v_lshrrev_b32_e32 v169, 1, v168
	v_add_u32_e32 v168, v168, v169
	v_mov_b32_e32 v169, 0
	v_mov_b32_e32 v251, 0
	v_lshl_add_u64 v[214:215], v[156:157], 0, v[168:169]
	v_lshl_add_u64 v[216:217], v[154:155], 0, v[168:169]
	v_mov_b32_e32 v250, 0x0
	v_lshl_add_u64 v[218:219], v[214:215], 0, v[250:251]
	global_load_dwordx4 v[164:167], v[218:219], off
	global_load_dwordx4 v[174:177], v[218:219], off offset:256
	v_mov_b32_e32 v250, 0x8000
	v_lshl_add_u64 v[218:219], v[214:215], 0, v[250:251]
	global_load_dwordx4 v[178:181], v[218:219], off
	global_load_dwordx4 v[182:185], v[218:219], off offset:256
	v_mov_b32_e32 v250, 0x10000
	v_lshl_add_u64 v[218:219], v[214:215], 0, v[250:251]
	global_load_dwordx4 v[186:189], v[218:219], off
	global_load_dwordx4 v[190:193], v[218:219], off offset:256
	v_mov_b32_e32 v250, 0x18000
	v_lshl_add_u64 v[218:219], v[214:215], 0, v[250:251]
	global_load_dwordx4 v[198:201], v[218:219], off
	global_load_dwordx4 v[202:205], v[218:219], off offset:256
	v_mov_b32_e32 v250, 0x40000
	v_lshl_add_u64 v[218:219], v[214:215], 0, v[250:251]
	global_load_dwordx4 v[206:209], v[218:219], off
	global_load_dwordx4 v[210:213], v[218:219], off offset:256
	s_waitcnt vmcnt(9)
	v_permlane16_swap_b32 v164, v166
	v_permlane16_swap_b32 v165, v167
	s_nop 1
	v_lshlrev_b32_e32 v242, 16, v164
	v_and_b32_e32 v243, 0xffff0000, v164
	v_lshlrev_b32_e32 v244, 16, v165
	v_and_b32_e32 v245, 0xffff0000, v165
	v_pk_fma_f32 v[126:127], v[126:127], v[142:143], v[242:243]
	v_pk_fma_f32 v[128:129], v[128:129], v[144:145], v[244:245]
	v_lshlrev_b32_e32 v246, 16, v166
	v_and_b32_e32 v247, 0xffff0000, v166
	v_lshlrev_b32_e32 v248, 16, v167
	v_and_b32_e32 v249, 0xffff0000, v167
	v_pk_fma_f32 v[122:123], v[122:123], v[138:139], v[246:247]
	v_pk_fma_f32 v[124:125], v[124:125], v[140:141], v[248:249]
	v_cvt_pk_bf16_f32 v126, v126, v127
	v_cvt_pk_bf16_f32 v127, v128, v129
	v_cvt_pk_bf16_f32 v128, v122, v123
	v_cvt_pk_bf16_f32 v129, v124, v125
	s_nop 1
	v_permlane16_swap_b32 v126, v128
	v_permlane16_swap_b32 v127, v129
	v_mov_b32_e32 v250, 0x0
	v_lshl_add_u64 v[220:221], v[216:217], 0, v[250:251]
	global_store_dwordx4 v[220:221], v[126:129], off
	v_mov_b32_e32 v250, 0x48000
	v_lshl_add_u64 v[218:219], v[214:215], 0, v[250:251]
	global_load_dwordx4 v[164:167], v[218:219], off
	s_waitcnt vmcnt(10)
	v_permlane16_swap_b32 v174, v176
	v_permlane16_swap_b32 v175, v177
	s_nop 1
	v_lshlrev_b32_e32 v242, 16, v174
	v_and_b32_e32 v243, 0xffff0000, v174
	v_lshlrev_b32_e32 v244, 16, v175
	v_and_b32_e32 v245, 0xffff0000, v175
	v_pk_fma_f32 v[118:119], v[118:119], v[134:135], v[242:243]
	v_pk_fma_f32 v[120:121], v[120:121], v[136:137], v[244:245]
	v_lshlrev_b32_e32 v246, 16, v176
	v_and_b32_e32 v247, 0xffff0000, v176
	v_lshlrev_b32_e32 v248, 16, v177
	v_and_b32_e32 v249, 0xffff0000, v177
	v_pk_fma_f32 v[110:111], v[110:111], v[130:131], v[246:247]
	v_pk_fma_f32 v[112:113], v[112:113], v[132:133], v[248:249]
	v_cvt_pk_bf16_f32 v118, v118, v119
	v_cvt_pk_bf16_f32 v119, v120, v121
	v_cvt_pk_bf16_f32 v120, v110, v111
	v_cvt_pk_bf16_f32 v121, v112, v113
	s_nop 1
	v_permlane16_swap_b32 v118, v120
	v_permlane16_swap_b32 v119, v121
	v_mov_b32_e32 v250, 0x0
	v_lshl_add_u64 v[220:221], v[216:217], 0, v[250:251]
	global_store_dwordx4 v[220:221], v[118:121], off offset:256
	global_load_dwordx4 v[174:177], v[218:219], off offset:256
	s_waitcnt vmcnt(11)
	v_permlane16_swap_b32 v178, v180
	v_permlane16_swap_b32 v179, v181
	s_nop 1
	v_lshlrev_b32_e32 v242, 16, v178
	v_and_b32_e32 v243, 0xffff0000, v178
	v_lshlrev_b32_e32 v244, 16, v179
	v_and_b32_e32 v245, 0xffff0000, v179
	v_pk_fma_f32 v[114:115], v[114:115], v[142:143], v[242:243]
	v_pk_fma_f32 v[116:117], v[116:117], v[144:145], v[244:245]
	v_lshlrev_b32_e32 v246, 16, v180
	v_and_b32_e32 v247, 0xffff0000, v180
	v_lshlrev_b32_e32 v248, 16, v181
	v_and_b32_e32 v249, 0xffff0000, v181
	v_pk_fma_f32 v[106:107], v[106:107], v[138:139], v[246:247]
	v_pk_fma_f32 v[108:109], v[108:109], v[140:141], v[248:249]
	v_cvt_pk_bf16_f32 v114, v114, v115
	v_cvt_pk_bf16_f32 v115, v116, v117
	v_cvt_pk_bf16_f32 v116, v106, v107
	v_cvt_pk_bf16_f32 v117, v108, v109
	s_nop 1
	v_permlane16_swap_b32 v114, v116
	v_permlane16_swap_b32 v115, v117
	v_mov_b32_e32 v250, 0x8000
	v_lshl_add_u64 v[220:221], v[216:217], 0, v[250:251]
	global_store_dwordx4 v[220:221], v[114:117], off
	v_mov_b32_e32 v250, 0x50000
	v_lshl_add_u64 v[218:219], v[214:215], 0, v[250:251]
	global_load_dwordx4 v[178:181], v[218:219], off
	s_waitcnt vmcnt(12)
	v_permlane16_swap_b32 v182, v184
	v_permlane16_swap_b32 v183, v185
	s_nop 1
	v_lshlrev_b32_e32 v242, 16, v182
	v_and_b32_e32 v243, 0xffff0000, v182
	v_lshlrev_b32_e32 v244, 16, v183
	v_and_b32_e32 v245, 0xffff0000, v183
	v_pk_fma_f32 v[102:103], v[102:103], v[134:135], v[242:243]
	v_pk_fma_f32 v[104:105], v[104:105], v[136:137], v[244:245]
	v_lshlrev_b32_e32 v246, 16, v184
	v_and_b32_e32 v247, 0xffff0000, v184
	v_lshlrev_b32_e32 v248, 16, v185
	v_and_b32_e32 v249, 0xffff0000, v185
	v_pk_fma_f32 v[98:99], v[98:99], v[130:131], v[246:247]
	v_pk_fma_f32 v[100:101], v[100:101], v[132:133], v[248:249]
	v_cvt_pk_bf16_f32 v102, v102, v103
	v_cvt_pk_bf16_f32 v103, v104, v105
	v_cvt_pk_bf16_f32 v104, v98, v99
	v_cvt_pk_bf16_f32 v105, v100, v101
	s_nop 1
	v_permlane16_swap_b32 v102, v104
	v_permlane16_swap_b32 v103, v105
	v_mov_b32_e32 v250, 0x8000
	v_lshl_add_u64 v[220:221], v[216:217], 0, v[250:251]
	global_store_dwordx4 v[220:221], v[102:105], off offset:256
	global_load_dwordx4 v[182:185], v[218:219], off offset:256
	s_waitcnt vmcnt(13)
	v_permlane16_swap_b32 v186, v188
	v_permlane16_swap_b32 v187, v189
	s_nop 1
	v_lshlrev_b32_e32 v242, 16, v186
	v_and_b32_e32 v243, 0xffff0000, v186
	v_lshlrev_b32_e32 v244, 16, v187
	v_and_b32_e32 v245, 0xffff0000, v187
	v_pk_fma_f32 v[94:95], v[94:95], v[142:143], v[242:243]
	v_pk_fma_f32 v[96:97], v[96:97], v[144:145], v[244:245]
	v_lshlrev_b32_e32 v246, 16, v188
	v_and_b32_e32 v247, 0xffff0000, v188
	v_lshlrev_b32_e32 v248, 16, v189
	v_and_b32_e32 v249, 0xffff0000, v189
	v_pk_fma_f32 v[90:91], v[90:91], v[138:139], v[246:247]
	v_pk_fma_f32 v[92:93], v[92:93], v[140:141], v[248:249]
	v_cvt_pk_bf16_f32 v94, v94, v95
	v_cvt_pk_bf16_f32 v95, v96, v97
	v_cvt_pk_bf16_f32 v96, v90, v91
	v_cvt_pk_bf16_f32 v97, v92, v93
	s_nop 1
	v_permlane16_swap_b32 v94, v96
	v_permlane16_swap_b32 v95, v97
	v_mov_b32_e32 v250, 0x10000
	v_lshl_add_u64 v[220:221], v[216:217], 0, v[250:251]
	global_store_dwordx4 v[220:221], v[94:97], off
	v_mov_b32_e32 v250, 0x58000
	v_lshl_add_u64 v[218:219], v[214:215], 0, v[250:251]
	global_load_dwordx4 v[186:189], v[218:219], off
	s_waitcnt vmcnt(14)
	v_permlane16_swap_b32 v190, v192
	v_permlane16_swap_b32 v191, v193
	s_nop 1
	v_lshlrev_b32_e32 v242, 16, v190
	v_and_b32_e32 v243, 0xffff0000, v190
	v_lshlrev_b32_e32 v244, 16, v191
	v_and_b32_e32 v245, 0xffff0000, v191
	v_pk_fma_f32 v[86:87], v[86:87], v[134:135], v[242:243]
	v_pk_fma_f32 v[88:89], v[88:89], v[136:137], v[244:245]
	v_lshlrev_b32_e32 v246, 16, v192
	v_and_b32_e32 v247, 0xffff0000, v192
	v_lshlrev_b32_e32 v248, 16, v193
	v_and_b32_e32 v249, 0xffff0000, v193
	v_pk_fma_f32 v[78:79], v[78:79], v[130:131], v[246:247]
	v_pk_fma_f32 v[80:81], v[80:81], v[132:133], v[248:249]
	v_cvt_pk_bf16_f32 v86, v86, v87
	v_cvt_pk_bf16_f32 v87, v88, v89
	v_cvt_pk_bf16_f32 v88, v78, v79
	v_cvt_pk_bf16_f32 v89, v80, v81
	s_nop 1
	v_permlane16_swap_b32 v86, v88
	v_permlane16_swap_b32 v87, v89
	v_mov_b32_e32 v250, 0x10000
	v_lshl_add_u64 v[220:221], v[216:217], 0, v[250:251]
	global_store_dwordx4 v[220:221], v[86:89], off offset:256
	global_load_dwordx4 v[190:193], v[218:219], off offset:256
	s_waitcnt vmcnt(15)
	v_permlane16_swap_b32 v198, v200
	v_permlane16_swap_b32 v199, v201
	s_nop 1
	v_lshlrev_b32_e32 v242, 16, v198
	v_and_b32_e32 v243, 0xffff0000, v198
	v_lshlrev_b32_e32 v244, 16, v199
	v_and_b32_e32 v245, 0xffff0000, v199
	v_pk_fma_f32 v[82:83], v[82:83], v[142:143], v[242:243]
	v_pk_fma_f32 v[84:85], v[84:85], v[144:145], v[244:245]
	v_lshlrev_b32_e32 v246, 16, v200
	v_and_b32_e32 v247, 0xffff0000, v200
	v_lshlrev_b32_e32 v248, 16, v201
	v_and_b32_e32 v249, 0xffff0000, v201
	v_pk_fma_f32 v[74:75], v[74:75], v[138:139], v[246:247]
	v_pk_fma_f32 v[76:77], v[76:77], v[140:141], v[248:249]
	v_cvt_pk_bf16_f32 v82, v82, v83
	v_cvt_pk_bf16_f32 v83, v84, v85
	v_cvt_pk_bf16_f32 v84, v74, v75
	v_cvt_pk_bf16_f32 v85, v76, v77
	s_nop 1
	v_permlane16_swap_b32 v82, v84
	v_permlane16_swap_b32 v83, v85
	v_mov_b32_e32 v250, 0x18000
	v_lshl_add_u64 v[220:221], v[216:217], 0, v[250:251]
	global_store_dwordx4 v[220:221], v[82:85], off
	s_waitcnt vmcnt(15)
	v_permlane16_swap_b32 v202, v204
	v_permlane16_swap_b32 v203, v205
	s_nop 1
	v_lshlrev_b32_e32 v242, 16, v202
	v_and_b32_e32 v243, 0xffff0000, v202
	v_lshlrev_b32_e32 v244, 16, v203
	v_and_b32_e32 v245, 0xffff0000, v203
	v_pk_fma_f32 v[70:71], v[70:71], v[134:135], v[242:243]
	v_pk_fma_f32 v[72:73], v[72:73], v[136:137], v[244:245]
	v_lshlrev_b32_e32 v246, 16, v204
	v_and_b32_e32 v247, 0xffff0000, v204
	v_lshlrev_b32_e32 v248, 16, v205
	v_and_b32_e32 v249, 0xffff0000, v205
	v_pk_fma_f32 v[66:67], v[66:67], v[130:131], v[246:247]
	v_pk_fma_f32 v[68:69], v[68:69], v[132:133], v[248:249]
	v_cvt_pk_bf16_f32 v70, v70, v71
	v_cvt_pk_bf16_f32 v71, v72, v73
	v_cvt_pk_bf16_f32 v72, v66, v67
	v_cvt_pk_bf16_f32 v73, v68, v69
	s_nop 1
	v_permlane16_swap_b32 v70, v72
	v_permlane16_swap_b32 v71, v73
	v_mov_b32_e32 v250, 0x18000
	v_lshl_add_u64 v[220:221], v[216:217], 0, v[250:251]
	global_store_dwordx4 v[220:221], v[70:73], off offset:256
	s_waitcnt vmcnt(15)
	v_permlane16_swap_b32 v206, v208
	v_permlane16_swap_b32 v207, v209
	s_nop 1
	v_lshlrev_b32_e32 v242, 16, v206
	v_and_b32_e32 v243, 0xffff0000, v206
	v_lshlrev_b32_e32 v244, 16, v207
	v_and_b32_e32 v245, 0xffff0000, v207
	v_pk_fma_f32 v[62:63], v[62:63], v[142:143], v[242:243]
	v_pk_fma_f32 v[64:65], v[64:65], v[144:145], v[244:245]
	v_lshlrev_b32_e32 v246, 16, v208
	v_and_b32_e32 v247, 0xffff0000, v208
	v_lshlrev_b32_e32 v248, 16, v209
	v_and_b32_e32 v249, 0xffff0000, v209
	v_pk_fma_f32 v[58:59], v[58:59], v[138:139], v[246:247]
	v_pk_fma_f32 v[60:61], v[60:61], v[140:141], v[248:249]
	v_cvt_pk_bf16_f32 v62, v62, v63
	v_cvt_pk_bf16_f32 v63, v64, v65
	v_cvt_pk_bf16_f32 v64, v58, v59
	v_cvt_pk_bf16_f32 v65, v60, v61
	s_nop 1
	v_permlane16_swap_b32 v62, v64
	v_permlane16_swap_b32 v63, v65
	v_mov_b32_e32 v250, 0x40000
	v_lshl_add_u64 v[220:221], v[216:217], 0, v[250:251]
	global_store_dwordx4 v[220:221], v[62:65], off
	s_waitcnt vmcnt(15)
	v_permlane16_swap_b32 v210, v212
	v_permlane16_swap_b32 v211, v213
	s_nop 1
	v_lshlrev_b32_e32 v242, 16, v210
	v_and_b32_e32 v243, 0xffff0000, v210
	v_lshlrev_b32_e32 v244, 16, v211
	v_and_b32_e32 v245, 0xffff0000, v211
	v_pk_fma_f32 v[54:55], v[54:55], v[134:135], v[242:243]
	v_pk_fma_f32 v[56:57], v[56:57], v[136:137], v[244:245]
	v_lshlrev_b32_e32 v246, 16, v212
	v_and_b32_e32 v247, 0xffff0000, v212
	v_lshlrev_b32_e32 v248, 16, v213
	v_and_b32_e32 v249, 0xffff0000, v213
	v_pk_fma_f32 v[44:45], v[44:45], v[130:131], v[246:247]
	v_pk_fma_f32 v[46:47], v[46:47], v[132:133], v[248:249]
	v_cvt_pk_bf16_f32 v54, v54, v55
	v_cvt_pk_bf16_f32 v55, v56, v57
	v_cvt_pk_bf16_f32 v56, v44, v45
	v_cvt_pk_bf16_f32 v57, v46, v47
	s_nop 1
	v_permlane16_swap_b32 v54, v56
	v_permlane16_swap_b32 v55, v57
	v_mov_b32_e32 v250, 0x40000
	v_lshl_add_u64 v[220:221], v[216:217], 0, v[250:251]
	global_store_dwordx4 v[220:221], v[54:57], off offset:256
	s_waitcnt vmcnt(14)
	v_permlane16_swap_b32 v164, v166
	v_permlane16_swap_b32 v165, v167
	s_nop 1
	v_lshlrev_b32_e32 v242, 16, v164
	v_and_b32_e32 v243, 0xffff0000, v164
	v_lshlrev_b32_e32 v244, 16, v165
	v_and_b32_e32 v245, 0xffff0000, v165
	v_pk_fma_f32 v[50:51], v[50:51], v[142:143], v[242:243]
	v_pk_fma_f32 v[52:53], v[52:53], v[144:145], v[244:245]
	v_lshlrev_b32_e32 v246, 16, v166
	v_and_b32_e32 v247, 0xffff0000, v166
	v_lshlrev_b32_e32 v248, 16, v167
	v_and_b32_e32 v249, 0xffff0000, v167
	v_pk_fma_f32 v[40:41], v[40:41], v[138:139], v[246:247]
	v_pk_fma_f32 v[42:43], v[42:43], v[140:141], v[248:249]
	v_cvt_pk_bf16_f32 v50, v50, v51
	v_cvt_pk_bf16_f32 v51, v52, v53
	v_cvt_pk_bf16_f32 v52, v40, v41
	v_cvt_pk_bf16_f32 v53, v42, v43
	s_nop 1
	v_permlane16_swap_b32 v50, v52
	v_permlane16_swap_b32 v51, v53
	v_mov_b32_e32 v250, 0x48000
	v_lshl_add_u64 v[220:221], v[216:217], 0, v[250:251]
	global_store_dwordx4 v[220:221], v[50:53], off
	s_waitcnt vmcnt(13)
	v_permlane16_swap_b32 v174, v176
	v_permlane16_swap_b32 v175, v177
	s_nop 1
	v_lshlrev_b32_e32 v242, 16, v174
	v_and_b32_e32 v243, 0xffff0000, v174
	v_lshlrev_b32_e32 v244, 16, v175
	v_and_b32_e32 v245, 0xffff0000, v175
	v_pk_fma_f32 v[36:37], v[36:37], v[134:135], v[242:243]
	v_pk_fma_f32 v[38:39], v[38:39], v[136:137], v[244:245]
	v_lshlrev_b32_e32 v246, 16, v176
	v_and_b32_e32 v247, 0xffff0000, v176
	v_lshlrev_b32_e32 v248, 16, v177
	v_and_b32_e32 v249, 0xffff0000, v177
	v_pk_fma_f32 v[28:29], v[28:29], v[130:131], v[246:247]
	v_pk_fma_f32 v[30:31], v[30:31], v[132:133], v[248:249]
	v_cvt_pk_bf16_f32 v36, v36, v37
	v_cvt_pk_bf16_f32 v37, v38, v39
	v_cvt_pk_bf16_f32 v38, v28, v29
	v_cvt_pk_bf16_f32 v39, v30, v31
	s_nop 1
	v_permlane16_swap_b32 v36, v38
	v_permlane16_swap_b32 v37, v39
	v_mov_b32_e32 v250, 0x48000
	v_lshl_add_u64 v[220:221], v[216:217], 0, v[250:251]
	global_store_dwordx4 v[220:221], v[36:39], off offset:256
	s_waitcnt vmcnt(12)
	v_permlane16_swap_b32 v178, v180
	v_permlane16_swap_b32 v179, v181
	s_nop 1
	v_lshlrev_b32_e32 v242, 16, v178
	v_and_b32_e32 v243, 0xffff0000, v178
	v_lshlrev_b32_e32 v244, 16, v179
	v_and_b32_e32 v245, 0xffff0000, v179
	v_pk_fma_f32 v[32:33], v[32:33], v[142:143], v[242:243]
	v_pk_fma_f32 v[34:35], v[34:35], v[144:145], v[244:245]
	v_lshlrev_b32_e32 v246, 16, v180
	v_and_b32_e32 v247, 0xffff0000, v180
	v_lshlrev_b32_e32 v248, 16, v181
	v_and_b32_e32 v249, 0xffff0000, v181
	v_pk_fma_f32 v[24:25], v[24:25], v[138:139], v[246:247]
	v_pk_fma_f32 v[26:27], v[26:27], v[140:141], v[248:249]
	v_cvt_pk_bf16_f32 v32, v32, v33
	v_cvt_pk_bf16_f32 v33, v34, v35
	v_cvt_pk_bf16_f32 v34, v24, v25
	v_cvt_pk_bf16_f32 v35, v26, v27
	s_nop 1
	v_permlane16_swap_b32 v32, v34
	v_permlane16_swap_b32 v33, v35
	v_mov_b32_e32 v250, 0x50000
	v_lshl_add_u64 v[220:221], v[216:217], 0, v[250:251]
	global_store_dwordx4 v[220:221], v[32:35], off
	s_waitcnt vmcnt(11)
	v_permlane16_swap_b32 v182, v184
	v_permlane16_swap_b32 v183, v185
	s_nop 1
	v_lshlrev_b32_e32 v242, 16, v182
	v_and_b32_e32 v243, 0xffff0000, v182
	v_lshlrev_b32_e32 v244, 16, v183
	v_and_b32_e32 v245, 0xffff0000, v183
	v_pk_fma_f32 v[20:21], v[20:21], v[134:135], v[242:243]
	v_pk_fma_f32 v[22:23], v[22:23], v[136:137], v[244:245]
	v_lshlrev_b32_e32 v246, 16, v184
	v_and_b32_e32 v247, 0xffff0000, v184
	v_lshlrev_b32_e32 v248, 16, v185
	v_and_b32_e32 v249, 0xffff0000, v185
	v_pk_fma_f32 v[12:13], v[12:13], v[130:131], v[246:247]
	v_pk_fma_f32 v[14:15], v[14:15], v[132:133], v[248:249]
	v_cvt_pk_bf16_f32 v20, v20, v21
	v_cvt_pk_bf16_f32 v21, v22, v23
	v_cvt_pk_bf16_f32 v22, v12, v13
	v_cvt_pk_bf16_f32 v23, v14, v15
	s_nop 1
	v_permlane16_swap_b32 v20, v22
	v_permlane16_swap_b32 v21, v23
	v_mov_b32_e32 v250, 0x50000
	v_lshl_add_u64 v[220:221], v[216:217], 0, v[250:251]
	global_store_dwordx4 v[220:221], v[20:23], off offset:256
	s_waitcnt vmcnt(10)
	v_permlane16_swap_b32 v186, v188
	v_permlane16_swap_b32 v187, v189
	s_nop 1
	v_lshlrev_b32_e32 v242, 16, v186
	v_and_b32_e32 v243, 0xffff0000, v186
	v_lshlrev_b32_e32 v244, 16, v187
	v_and_b32_e32 v245, 0xffff0000, v187
	v_pk_fma_f32 v[16:17], v[16:17], v[142:143], v[242:243]
	v_pk_fma_f32 v[18:19], v[18:19], v[144:145], v[244:245]
	v_lshlrev_b32_e32 v246, 16, v188
	v_and_b32_e32 v247, 0xffff0000, v188
	v_lshlrev_b32_e32 v248, 16, v189
	v_and_b32_e32 v249, 0xffff0000, v189
	v_pk_fma_f32 v[8:9], v[8:9], v[138:139], v[246:247]
	v_pk_fma_f32 v[10:11], v[10:11], v[140:141], v[248:249]
	v_cvt_pk_bf16_f32 v16, v16, v17
	v_cvt_pk_bf16_f32 v17, v18, v19
	v_cvt_pk_bf16_f32 v18, v8, v9
	v_cvt_pk_bf16_f32 v19, v10, v11
	s_nop 1
	v_permlane16_swap_b32 v16, v18
	v_permlane16_swap_b32 v17, v19
	v_mov_b32_e32 v250, 0x58000
	v_lshl_add_u64 v[220:221], v[216:217], 0, v[250:251]
	global_store_dwordx4 v[220:221], v[16:19], off
	s_waitcnt vmcnt(9)
	v_permlane16_swap_b32 v190, v192
	v_permlane16_swap_b32 v191, v193
	s_nop 1
	v_lshlrev_b32_e32 v242, 16, v190
	v_and_b32_e32 v243, 0xffff0000, v190
	v_lshlrev_b32_e32 v244, 16, v191
	v_and_b32_e32 v245, 0xffff0000, v191
	v_pk_fma_f32 v[4:5], v[4:5], v[134:135], v[242:243]
	v_pk_fma_f32 v[6:7], v[6:7], v[136:137], v[244:245]
	v_lshlrev_b32_e32 v246, 16, v192
	v_and_b32_e32 v247, 0xffff0000, v192
	v_lshlrev_b32_e32 v248, 16, v193
	v_and_b32_e32 v249, 0xffff0000, v193
	v_pk_fma_f32 v[0:1], v[0:1], v[130:131], v[246:247]
	v_pk_fma_f32 v[2:3], v[2:3], v[132:133], v[248:249]
	v_cvt_pk_bf16_f32 v4, v4, v5
	v_cvt_pk_bf16_f32 v5, v6, v7
	v_cvt_pk_bf16_f32 v6, v0, v1
	v_cvt_pk_bf16_f32 v7, v2, v3
	s_nop 1
	v_permlane16_swap_b32 v4, v6
	v_permlane16_swap_b32 v5, v7
	v_mov_b32_e32 v250, 0x58000
	v_lshl_add_u64 v[220:221], v[216:217], 0, v[250:251]
	global_store_dwordx4 v[220:221], v[4:7], off offset:256
	s_and_b64 vcc, exec, s[0:1]
	s_mov_b32 s22, s14
	s_mov_b32 s24, s16
	s_cbranch_vccnz .LBB0_1205

.LBB0_1215:
	s_mul_i32 s15, s24, 0x1800
	s_mul_hi_i32 s17, s24, 0x1800
	s_and_b64 s[24:25], s[26:27], exec
	s_cselect_b32 s25, 0, s17
	s_cselect_b32 s24, 0x30000, s15
	v_lshl_or_b32 v204, s23, 8, v209
	s_ashr_i32 s23, s22, 31
	s_lshl_b64 s[26:27], s[28:29], 2
	s_add_u32 s26, s30, s26
	s_addc_u32 s27, s31, s27
	s_lshl_b64 s[22:23], s[22:23], 19
	v_lshl_add_u64 v[250:251], v[198:199], 0, s[22:23]
	s_lshl_b64 s[22:23], s[24:25], 2
	v_ashrrev_i32_e32 v205, 31, v204
	s_add_u32 s22, s45, s22
	v_lshl_add_u64 v[146:147], s[26:27], 0, v[192:193]
	s_addc_u32 s23, s46, s23
	v_lshlrev_b64 v[148:149], 2, v[204:205]
	v_lshl_add_u64 v[130:131], s[22:23], 0, v[148:149]
	v_lshl_add_u64 v[206:207], v[146:147], 0, v[148:149]
	global_load_dwordx4 v[142:145], v[130:131], off
	global_load_dwordx4 v[138:141], v[130:131], off offset:64
	global_load_dwordx4 v[134:137], v[130:131], off offset:512
	s_nop 0
	global_load_dwordx4 v[130:133], v[130:131], off offset:576
	s_nop 0
	s_mov_b32 s15, 0x20000
	s_nop 0
	s_mov_b32 s15, 0x30000
	s_nop 0
	v_lshl_add_u64 v[204:205], v[204:205], 1, v[250:251]
	s_nop 0
	s_nop 0
	s_mov_b32 s15, 0x80000
	s_mov_b32 s23, s14
	s_mov_b32 s22, s16
	s_mov_b64 s[26:27], s[20:21]
	s_mov_b64 s[24:25], s[18:19]
	v_and_b32_e32 v188, 16, v224
	v_lshrrev_b32_e32 v189, 1, v188
	v_add_u32_e32 v188, v188, v189
	v_mov_b32_e32 v189, 0
	v_mov_b32_e32 v221, 0
	v_lshl_add_u64 v[150:151], v[204:205], 0, v[188:189]
	v_mov_b32_e32 v220, 0x0
	v_lshl_add_u64 v[152:153], v[206:207], 0, v[220:221]
	global_load_dwordx4 v[242:245], v[152:153], off
	global_load_dwordx4 v[246:249], v[152:153], off offset:64
	global_load_dwordx4 v[212:215], v[152:153], off offset:512
	global_load_dwordx4 v[216:219], v[152:153], off offset:576
	v_mov_b32_e32 v220, 0x10000
	v_lshl_add_u64 v[152:153], v[206:207], 0, v[220:221]
	global_load_dwordx4 v[164:167], v[152:153], off
	global_load_dwordx4 v[168:171], v[152:153], off offset:64
	global_load_dwordx4 v[172:175], v[152:153], off offset:512
	global_load_dwordx4 v[176:179], v[152:153], off offset:576
	v_mov_b32_e32 v220, 0x20000
	v_lshl_add_u64 v[152:153], v[206:207], 0, v[220:221]
	global_load_dwordx4 v[180:183], v[152:153], off
	global_load_dwordx4 v[184:187], v[152:153], off offset:64
	s_waitcnt vmcnt(8)
	v_pk_fma_f32 v[126:127], v[126:127], v[142:143], v[242:243]
	v_pk_fma_f32 v[128:129], v[128:129], v[144:145], v[244:245]
	v_pk_fma_f32 v[122:123], v[122:123], v[138:139], v[246:247]
	v_pk_fma_f32 v[124:125], v[124:125], v[140:141], v[248:249]
	v_cvt_pk_bf16_f32 v126, v126, v127
	v_cvt_pk_bf16_f32 v127, v128, v129
	v_cvt_pk_bf16_f32 v128, v122, v123
	v_cvt_pk_bf16_f32 v129, v124, v125
	s_nop 1
	v_permlane16_swap_b32 v126, v128
	v_permlane16_swap_b32 v127, v129
	v_mov_b32_e32 v220, 0x0
	v_lshl_add_u64 v[154:155], v[150:151], 0, v[220:221]
	global_store_dwordx4 v[154:155], v[126:129], off
	global_load_dwordx4 v[242:245], v[152:153], off offset:512
	global_load_dwordx4 v[246:249], v[152:153], off offset:576
	s_waitcnt vmcnt(9)
	v_pk_fma_f32 v[114:115], v[114:115], v[134:135], v[212:213]
	v_pk_fma_f32 v[116:117], v[116:117], v[136:137], v[214:215]
	v_pk_fma_f32 v[110:111], v[110:111], v[130:131], v[216:217]
	v_pk_fma_f32 v[112:113], v[112:113], v[132:133], v[218:219]
	v_cvt_pk_bf16_f32 v114, v114, v115
	v_cvt_pk_bf16_f32 v115, v116, v117
	v_cvt_pk_bf16_f32 v116, v110, v111
	v_cvt_pk_bf16_f32 v117, v112, v113
	s_nop 1
	v_permlane16_swap_b32 v114, v116
	v_permlane16_swap_b32 v115, v117
	v_mov_b32_e32 v220, 0x0
	v_lshl_add_u64 v[154:155], v[150:151], 0, v[220:221]
	global_store_dwordx4 v[154:155], v[114:117], off offset:256
	v_mov_b32_e32 v220, 0x30000
	v_lshl_add_u64 v[152:153], v[206:207], 0, v[220:221]
	global_load_dwordx4 v[212:215], v[152:153], off
	global_load_dwordx4 v[216:219], v[152:153], off offset:64
	s_waitcnt vmcnt(10)
	v_pk_fma_f32 v[118:119], v[118:119], v[142:143], v[164:165]
	v_pk_fma_f32 v[120:121], v[120:121], v[144:145], v[166:167]
	v_pk_fma_f32 v[106:107], v[106:107], v[138:139], v[168:169]
	v_pk_fma_f32 v[108:109], v[108:109], v[140:141], v[170:171]
	v_cvt_pk_bf16_f32 v118, v118, v119
	v_cvt_pk_bf16_f32 v119, v120, v121
	v_cvt_pk_bf16_f32 v120, v106, v107
	v_cvt_pk_bf16_f32 v121, v108, v109
	s_nop 1
	v_permlane16_swap_b32 v118, v120
	v_permlane16_swap_b32 v119, v121
	v_mov_b32_e32 v220, 0x8000
	v_lshl_add_u64 v[154:155], v[150:151], 0, v[220:221]
	global_store_dwordx4 v[154:155], v[118:121], off
	global_load_dwordx4 v[164:167], v[152:153], off offset:512
	global_load_dwordx4 v[168:171], v[152:153], off offset:576
	s_waitcnt vmcnt(11)
	v_pk_fma_f32 v[102:103], v[102:103], v[134:135], v[172:173]
	v_pk_fma_f32 v[104:105], v[104:105], v[136:137], v[174:175]
	v_pk_fma_f32 v[98:99], v[98:99], v[130:131], v[176:177]
	v_pk_fma_f32 v[100:101], v[100:101], v[132:133], v[178:179]
	v_cvt_pk_bf16_f32 v102, v102, v103
	v_cvt_pk_bf16_f32 v103, v104, v105
	v_cvt_pk_bf16_f32 v104, v98, v99
	v_cvt_pk_bf16_f32 v105, v100, v101
	s_nop 1
	v_permlane16_swap_b32 v102, v104
	v_permlane16_swap_b32 v103, v105
	v_mov_b32_e32 v220, 0x8000
	v_lshl_add_u64 v[154:155], v[150:151], 0, v[220:221]
	global_store_dwordx4 v[154:155], v[102:105], off offset:256
	v_mov_b32_e32 v220, 0x80000
	v_lshl_add_u64 v[152:153], v[206:207], 0, v[220:221]
	global_load_dwordx4 v[172:175], v[152:153], off
	global_load_dwordx4 v[176:179], v[152:153], off offset:64
	s_waitcnt vmcnt(12)
	v_pk_fma_f32 v[94:95], v[94:95], v[142:143], v[180:181]
	v_pk_fma_f32 v[96:97], v[96:97], v[144:145], v[182:183]
	v_pk_fma_f32 v[90:91], v[90:91], v[138:139], v[184:185]
	v_pk_fma_f32 v[92:93], v[92:93], v[140:141], v[186:187]
	v_cvt_pk_bf16_f32 v94, v94, v95
	v_cvt_pk_bf16_f32 v95, v96, v97
	v_cvt_pk_bf16_f32 v96, v90, v91
	v_cvt_pk_bf16_f32 v97, v92, v93
	s_nop 1
	v_permlane16_swap_b32 v94, v96
	v_permlane16_swap_b32 v95, v97
	v_mov_b32_e32 v220, 0x10000
	v_lshl_add_u64 v[154:155], v[150:151], 0, v[220:221]
	global_store_dwordx4 v[154:155], v[94:97], off
	global_load_dwordx4 v[180:183], v[152:153], off offset:512
	global_load_dwordx4 v[184:187], v[152:153], off offset:576
	s_waitcnt vmcnt(12)
	v_pk_fma_f32 v[82:83], v[82:83], v[134:135], v[242:243]
	v_pk_fma_f32 v[84:85], v[84:85], v[136:137], v[244:245]
	v_pk_fma_f32 v[78:79], v[78:79], v[130:131], v[246:247]
	v_pk_fma_f32 v[80:81], v[80:81], v[132:133], v[248:249]
	v_cvt_pk_bf16_f32 v82, v82, v83
	v_cvt_pk_bf16_f32 v83, v84, v85
	v_cvt_pk_bf16_f32 v84, v78, v79
	v_cvt_pk_bf16_f32 v85, v80, v81
	s_nop 1
	v_permlane16_swap_b32 v82, v84
	v_permlane16_swap_b32 v83, v85
	v_mov_b32_e32 v220, 0x10000
	v_lshl_add_u64 v[154:155], v[150:151], 0, v[220:221]
	global_store_dwordx4 v[154:155], v[82:85], off offset:256
	v_mov_b32_e32 v220, 0x90000
	v_lshl_add_u64 v[152:153], v[206:207], 0, v[220:221]
	global_load_dwordx4 v[242:245], v[152:153], off
	global_load_dwordx4 v[246:249], v[152:153], off offset:64
	s_waitcnt vmcnt(12)
	v_pk_fma_f32 v[86:87], v[86:87], v[142:143], v[212:213]
	v_pk_fma_f32 v[88:89], v[88:89], v[144:145], v[214:215]
	v_pk_fma_f32 v[74:75], v[74:75], v[138:139], v[216:217]
	v_pk_fma_f32 v[76:77], v[76:77], v[140:141], v[218:219]
	v_cvt_pk_bf16_f32 v86, v86, v87
	v_cvt_pk_bf16_f32 v87, v88, v89
	v_cvt_pk_bf16_f32 v88, v74, v75
	v_cvt_pk_bf16_f32 v89, v76, v77
	s_nop 1
	v_permlane16_swap_b32 v86, v88
	v_permlane16_swap_b32 v87, v89
	v_mov_b32_e32 v220, 0x18000
	v_lshl_add_u64 v[154:155], v[150:151], 0, v[220:221]
	global_store_dwordx4 v[154:155], v[86:89], off
	global_load_dwordx4 v[212:215], v[152:153], off offset:512
	global_load_dwordx4 v[216:219], v[152:153], off offset:576
	s_waitcnt vmcnt(12)
	v_pk_fma_f32 v[70:71], v[70:71], v[134:135], v[164:165]
	v_pk_fma_f32 v[72:73], v[72:73], v[136:137], v[166:167]
	v_pk_fma_f32 v[66:67], v[66:67], v[130:131], v[168:169]
	v_pk_fma_f32 v[68:69], v[68:69], v[132:133], v[170:171]
	v_cvt_pk_bf16_f32 v70, v70, v71
	v_cvt_pk_bf16_f32 v71, v72, v73
	v_cvt_pk_bf16_f32 v72, v66, v67
	v_cvt_pk_bf16_f32 v73, v68, v69
	s_nop 1
	v_permlane16_swap_b32 v70, v72
	v_permlane16_swap_b32 v71, v73
	v_mov_b32_e32 v220, 0x18000
	v_lshl_add_u64 v[154:155], v[150:151], 0, v[220:221]
	global_store_dwordx4 v[154:155], v[70:73], off offset:256
	v_mov_b32_e32 v220, 0xa0000
	v_lshl_add_u64 v[152:153], v[206:207], 0, v[220:221]
	global_load_dwordx4 v[164:167], v[152:153], off
	global_load_dwordx4 v[168:171], v[152:153], off offset:64
	s_waitcnt vmcnt(12)
	v_pk_fma_f32 v[62:63], v[62:63], v[142:143], v[172:173]
	v_pk_fma_f32 v[64:65], v[64:65], v[144:145], v[174:175]
	v_pk_fma_f32 v[58:59], v[58:59], v[138:139], v[176:177]
	v_pk_fma_f32 v[60:61], v[60:61], v[140:141], v[178:179]
	v_cvt_pk_bf16_f32 v62, v62, v63
	v_cvt_pk_bf16_f32 v63, v64, v65
	v_cvt_pk_bf16_f32 v64, v58, v59
	v_cvt_pk_bf16_f32 v65, v60, v61
	s_nop 1
	v_permlane16_swap_b32 v62, v64
	v_permlane16_swap_b32 v63, v65
	v_mov_b32_e32 v220, 0x40000
	v_lshl_add_u64 v[154:155], v[150:151], 0, v[220:221]
	global_store_dwordx4 v[154:155], v[62:65], off
	global_load_dwordx4 v[172:175], v[152:153], off offset:512
	global_load_dwordx4 v[176:179], v[152:153], off offset:576
	s_waitcnt vmcnt(12)
	v_pk_fma_f32 v[50:51], v[50:51], v[134:135], v[180:181]
	v_pk_fma_f32 v[52:53], v[52:53], v[136:137], v[182:183]
	v_pk_fma_f32 v[44:45], v[44:45], v[130:131], v[184:185]
	v_pk_fma_f32 v[46:47], v[46:47], v[132:133], v[186:187]
	v_cvt_pk_bf16_f32 v50, v50, v51
	v_cvt_pk_bf16_f32 v51, v52, v53
	v_cvt_pk_bf16_f32 v52, v44, v45
	v_cvt_pk_bf16_f32 v53, v46, v47
	s_nop 1
	v_permlane16_swap_b32 v50, v52
	v_permlane16_swap_b32 v51, v53
	v_mov_b32_e32 v220, 0x40000
	v_lshl_add_u64 v[154:155], v[150:151], 0, v[220:221]
	global_store_dwordx4 v[154:155], v[50:53], off offset:256
	v_mov_b32_e32 v220, 0xb0000
	v_lshl_add_u64 v[152:153], v[206:207], 0, v[220:221]
	global_load_dwordx4 v[180:183], v[152:153], off
	global_load_dwordx4 v[184:187], v[152:153], off offset:64
	s_waitcnt vmcnt(12)
	v_pk_fma_f32 v[54:55], v[54:55], v[142:143], v[242:243]
	v_pk_fma_f32 v[56:57], v[56:57], v[144:145], v[244:245]
	v_pk_fma_f32 v[40:41], v[40:41], v[138:139], v[246:247]
	v_pk_fma_f32 v[42:43], v[42:43], v[140:141], v[248:249]
	v_cvt_pk_bf16_f32 v54, v54, v55
	v_cvt_pk_bf16_f32 v55, v56, v57
	v_cvt_pk_bf16_f32 v56, v40, v41
	v_cvt_pk_bf16_f32 v57, v42, v43
	s_nop 1
	v_permlane16_swap_b32 v54, v56
	v_permlane16_swap_b32 v55, v57
	v_mov_b32_e32 v220, 0x48000
	v_lshl_add_u64 v[154:155], v[150:151], 0, v[220:221]
	global_store_dwordx4 v[154:155], v[54:57], off
	global_load_dwordx4 v[242:245], v[152:153], off offset:512
	global_load_dwordx4 v[246:249], v[152:153], off offset:576
	s_waitcnt vmcnt(12)
	v_pk_fma_f32 v[32:33], v[32:33], v[134:135], v[212:213]
	v_pk_fma_f32 v[34:35], v[34:35], v[136:137], v[214:215]
	v_pk_fma_f32 v[28:29], v[28:29], v[130:131], v[216:217]
	v_pk_fma_f32 v[30:31], v[30:31], v[132:133], v[218:219]
	v_cvt_pk_bf16_f32 v32, v32, v33
	v_cvt_pk_bf16_f32 v33, v34, v35
	v_cvt_pk_bf16_f32 v34, v28, v29
	v_cvt_pk_bf16_f32 v35, v30, v31
	s_nop 1
	v_permlane16_swap_b32 v32, v34
	v_permlane16_swap_b32 v33, v35
	v_mov_b32_e32 v220, 0x48000
	v_lshl_add_u64 v[154:155], v[150:151], 0, v[220:221]
	global_store_dwordx4 v[154:155], v[32:35], off offset:256
	s_waitcnt vmcnt(10)
	v_pk_fma_f32 v[36:37], v[36:37], v[142:143], v[164:165]
	v_pk_fma_f32 v[38:39], v[38:39], v[144:145], v[166:167]
	v_pk_fma_f32 v[24:25], v[24:25], v[138:139], v[168:169]
	v_pk_fma_f32 v[26:27], v[26:27], v[140:141], v[170:171]
	v_cvt_pk_bf16_f32 v36, v36, v37
	v_cvt_pk_bf16_f32 v37, v38, v39
	v_cvt_pk_bf16_f32 v38, v24, v25
	v_cvt_pk_bf16_f32 v39, v26, v27
	s_nop 1
	v_permlane16_swap_b32 v36, v38
	v_permlane16_swap_b32 v37, v39
	v_mov_b32_e32 v220, 0x50000
	v_lshl_add_u64 v[154:155], v[150:151], 0, v[220:221]
	global_store_dwordx4 v[154:155], v[36:39], off
	s_waitcnt vmcnt(8)
	v_pk_fma_f32 v[16:17], v[16:17], v[134:135], v[172:173]
	v_pk_fma_f32 v[18:19], v[18:19], v[136:137], v[174:175]
	v_pk_fma_f32 v[12:13], v[12:13], v[130:131], v[176:177]
	v_pk_fma_f32 v[14:15], v[14:15], v[132:133], v[178:179]
	v_cvt_pk_bf16_f32 v16, v16, v17
	v_cvt_pk_bf16_f32 v17, v18, v19
	v_cvt_pk_bf16_f32 v18, v12, v13
	v_cvt_pk_bf16_f32 v19, v14, v15
	s_nop 1
	v_permlane16_swap_b32 v16, v18
	v_permlane16_swap_b32 v17, v19
	v_mov_b32_e32 v220, 0x50000
	v_lshl_add_u64 v[154:155], v[150:151], 0, v[220:221]
	global_store_dwordx4 v[154:155], v[16:19], off offset:256
	s_waitcnt vmcnt(6)
	v_pk_fma_f32 v[20:21], v[20:21], v[142:143], v[180:181]
	v_pk_fma_f32 v[22:23], v[22:23], v[144:145], v[182:183]
	v_pk_fma_f32 v[8:9], v[8:9], v[138:139], v[184:185]
	v_pk_fma_f32 v[10:11], v[10:11], v[140:141], v[186:187]
	v_cvt_pk_bf16_f32 v20, v20, v21
	v_cvt_pk_bf16_f32 v21, v22, v23
	v_cvt_pk_bf16_f32 v22, v8, v9
	v_cvt_pk_bf16_f32 v23, v10, v11
	s_nop 1
	v_permlane16_swap_b32 v20, v22
	v_permlane16_swap_b32 v21, v23
	v_mov_b32_e32 v220, 0x58000
	v_lshl_add_u64 v[154:155], v[150:151], 0, v[220:221]
	global_store_dwordx4 v[154:155], v[20:23], off
	s_waitcnt vmcnt(4)
	v_pk_fma_f32 v[4:5], v[4:5], v[134:135], v[242:243]
	v_pk_fma_f32 v[6:7], v[6:7], v[136:137], v[244:245]
	v_pk_fma_f32 v[0:1], v[0:1], v[130:131], v[246:247]
	v_pk_fma_f32 v[2:3], v[2:3], v[132:133], v[248:249]
	v_cvt_pk_bf16_f32 v4, v4, v5
	v_cvt_pk_bf16_f32 v5, v6, v7
	v_cvt_pk_bf16_f32 v6, v0, v1
	v_cvt_pk_bf16_f32 v7, v2, v3
	s_nop 1
	v_permlane16_swap_b32 v4, v6
	v_permlane16_swap_b32 v5, v7
	v_mov_b32_e32 v220, 0x58000
	v_lshl_add_u64 v[154:155], v[150:151], 0, v[220:221]
	global_store_dwordx4 v[154:155], v[4:7], off offset:256
	s_mov_b32 s15, 0x90000
	s_mov_b32 s15, 0xa0000
	s_mov_b32 s15, 0xb0000
	s_mov_b32 s15, 0x40000
	s_mov_b32 s15, 0x48000
	s_mov_b32 s15, 0x50000
	s_mov_b32 s15, 0x58000
	s_and_b64 vcc, exec, s[0:1]
	s_cbranch_vccnz .LBB0_1223

.LBB0_1421:
	s_add_u32 s18, s16, 0x100
	s_addc_u32 s19, s17, 0
	s_add_i32 s47, 0, 0x10000
	v_add_u32_e32 v142, s47, v204
	ds_read_b128 v[130:133], v142
	ds_read_b128 v[134:137], v142 offset:1024
	ds_read_b128 v[138:141], v142 offset:2048
	ds_read_b128 v[142:145], v142 offset:3072
	s_cmp_eq_u32 s46, 40
	s_cselect_b32 s23, s11, s19
	s_cselect_b32 s22, s10, s18
	s_cselect_b32 s21, s13, s45
	s_cselect_b32 s20, s12, s44
	v_lshl_add_u64 v[188:189], s[16:17], 0, v[152:153]
	s_add_i32 m0, s31, 0xc000
	ds_read_b128 v[156:159], v206
	ds_read_b128 v[160:163], v206 offset:1024
	ds_read_b128 v[164:167], v206 offset:2048
	ds_read_b128 v[168:171], v206 offset:3072
	ds_read_b128 v[172:175], v206 offset:4096
	ds_read_b128 v[176:179], v206 offset:5120
	ds_read_b128 v[180:183], v206 offset:6144
	ds_read_b128 v[184:187], v206 offset:7168
	global_load_lds_dwordx4 v[188:189], off
	v_lshl_add_u64 v[188:189], s[16:17], 0, v[154:155]
	s_add_i32 m0, s31, 0xe000
	s_nop 0
	global_load_lds_dwordx4 v[188:189], off
	s_waitcnt lgkmcnt(8)
	s_barrier
	s_waitcnt lgkmcnt(0)
	s_setprio 1
	s_waitcnt lgkmcnt(0)
	v_mfma_f32_16x16x32_bf16 v[126:129], v[130:133], v[156:159], v[126:129]
	v_mfma_f32_16x16x32_bf16 v[122:125], v[138:141], v[156:159], v[122:125]
	v_mfma_f32_16x16x32_bf16 v[114:117], v[130:133], v[164:167], v[114:117]
	v_mfma_f32_16x16x32_bf16 v[106:109], v[138:141], v[164:167], v[106:109]
	v_mfma_f32_16x16x32_bf16 v[98:101], v[130:133], v[172:175], v[98:101]
	v_mfma_f32_16x16x32_bf16 v[90:93], v[138:141], v[172:175], v[90:93]
	v_mfma_f32_16x16x32_bf16 v[82:85], v[130:133], v[180:183], v[82:85]
	v_mfma_f32_16x16x32_bf16 v[74:77], v[138:141], v[180:183], v[74:77]
	v_mfma_f32_16x16x32_bf16 v[126:129], v[134:137], v[160:163], v[126:129]
	v_mfma_f32_16x16x32_bf16 v[122:125], v[142:145], v[160:163], v[122:125]
	v_mfma_f32_16x16x32_bf16 v[114:117], v[134:137], v[168:171], v[114:117]
	v_mfma_f32_16x16x32_bf16 v[106:109], v[142:145], v[168:171], v[106:109]
	v_mfma_f32_16x16x32_bf16 v[98:101], v[134:137], v[176:179], v[98:101]
	v_mfma_f32_16x16x32_bf16 v[90:93], v[142:145], v[176:179], v[90:93]
	v_mfma_f32_16x16x32_bf16 v[82:85], v[134:137], v[184:187], v[82:85]
	v_mfma_f32_16x16x32_bf16 v[74:77], v[142:145], v[184:187], v[74:77]
	s_setprio 0
	s_barrier
	s_add_i32 s48, 0, 0x14000
	v_add_u32_e32 v192, s48, v204
	s_add_i32 s16, s47, s25
	ds_read_b128 v[188:191], v192
	ds_read_b128 v[198:201], v192 offset:1024
	ds_read_b128 v[208:211], v192 offset:2048
	ds_read_b128 v[212:215], v192 offset:3072
	v_lshl_add_u64 v[192:193], s[20:21], 0, v[48:49]
	s_mov_b32 m0, s16
	v_lshl_add_u64 v[202:203], s[20:21], 0, v[146:147]
	global_load_lds_dwordx4 v[192:193], off
	s_add_i32 m0, s16, 0x2000
	s_nop 0
	global_load_lds_dwordx4 v[202:203], off
	s_barrier
	s_waitcnt lgkmcnt(0)
	s_setprio 1
	s_waitcnt lgkmcnt(0)
	v_mfma_f32_16x16x32_bf16 v[118:121], v[188:191], v[156:159], v[118:121]
	v_mfma_f32_16x16x32_bf16 v[110:113], v[208:211], v[156:159], v[110:113]
	v_mfma_f32_16x16x32_bf16 v[102:105], v[188:191], v[164:167], v[102:105]
	v_mfma_f32_16x16x32_bf16 v[94:97], v[208:211], v[164:167], v[94:97]
	v_mfma_f32_16x16x32_bf16 v[86:89], v[188:191], v[172:175], v[86:89]
	v_mfma_f32_16x16x32_bf16 v[78:81], v[208:211], v[172:175], v[78:81]
	v_mfma_f32_16x16x32_bf16 v[70:73], v[188:191], v[180:183], v[70:73]
	v_mfma_f32_16x16x32_bf16 v[66:69], v[208:211], v[180:183], v[66:69]
	v_mfma_f32_16x16x32_bf16 v[118:121], v[198:201], v[160:163], v[118:121]
	v_mfma_f32_16x16x32_bf16 v[110:113], v[212:215], v[160:163], v[110:113]
	v_mfma_f32_16x16x32_bf16 v[102:105], v[198:201], v[168:171], v[102:105]
	v_mfma_f32_16x16x32_bf16 v[94:97], v[212:215], v[168:171], v[94:97]
	v_mfma_f32_16x16x32_bf16 v[86:89], v[198:201], v[176:179], v[86:89]
	v_mfma_f32_16x16x32_bf16 v[78:81], v[212:215], v[176:179], v[78:81]
	v_mfma_f32_16x16x32_bf16 v[70:73], v[198:201], v[184:187], v[70:73]
	v_mfma_f32_16x16x32_bf16 v[66:69], v[212:215], v[184:187], v[66:69]
	s_setprio 0
	s_mov_b32 m0, s31
	v_lshl_add_u64 v[216:217], s[22:23], 0, v[48:49]
	s_barrier
	ds_read_b128 v[156:159], v206 offset:16384
	ds_read_b128 v[160:163], v206 offset:17408
	ds_read_b128 v[164:167], v206 offset:18432
	ds_read_b128 v[168:171], v206 offset:19456
	ds_read_b128 v[172:175], v206 offset:20480
	ds_read_b128 v[176:179], v206 offset:21504
	ds_read_b128 v[180:183], v206 offset:22528
	ds_read_b128 v[184:187], v206 offset:23552
	global_load_lds_dwordx4 v[216:217], off
	v_lshl_add_u64 v[218:219], s[22:23], 0, v[146:147]
	s_mov_b32 m0, s34
	s_nop 0
	global_load_lds_dwordx4 v[218:219], off
	s_barrier
	s_waitcnt lgkmcnt(0)
	s_setprio 1
	s_waitcnt lgkmcnt(0)
	v_mfma_f32_16x16x32_bf16 v[62:65], v[130:133], v[156:159], v[62:65]
	v_mfma_f32_16x16x32_bf16 v[58:61], v[138:141], v[156:159], v[58:61]
	v_mfma_f32_16x16x32_bf16 v[50:53], v[130:133], v[164:167], v[50:53]
	v_mfma_f32_16x16x32_bf16 v[40:43], v[138:141], v[164:167], v[40:43]
	v_mfma_f32_16x16x32_bf16 v[32:35], v[130:133], v[172:175], v[32:35]
	v_mfma_f32_16x16x32_bf16 v[24:27], v[138:141], v[172:175], v[24:27]
	v_mfma_f32_16x16x32_bf16 v[16:19], v[130:133], v[180:183], v[16:19]
	v_mfma_f32_16x16x32_bf16 v[8:11], v[138:141], v[180:183], v[8:11]
	v_mfma_f32_16x16x32_bf16 v[62:65], v[134:137], v[160:163], v[62:65]
	v_mfma_f32_16x16x32_bf16 v[58:61], v[142:145], v[160:163], v[58:61]
	v_mfma_f32_16x16x32_bf16 v[50:53], v[134:137], v[168:171], v[50:53]
	v_mfma_f32_16x16x32_bf16 v[40:43], v[142:145], v[168:171], v[40:43]
	v_mfma_f32_16x16x32_bf16 v[32:35], v[134:137], v[176:179], v[32:35]
	v_mfma_f32_16x16x32_bf16 v[24:27], v[142:145], v[176:179], v[24:27]
	v_mfma_f32_16x16x32_bf16 v[16:19], v[134:137], v[184:187], v[16:19]
	v_mfma_f32_16x16x32_bf16 v[8:11], v[142:145], v[184:187], v[8:11]
	s_setprio 0
	s_barrier
	s_add_u32 s16, s20, 0xb0000
	s_addc_u32 s17, s21, 0
	s_add_i32 s47, s48, s25
	v_lshl_add_u64 v[130:131], s[16:17], 0, v[48:49]
	s_mov_b32 m0, s47
	s_nop 0
	global_load_lds_dwordx4 v[130:131], off
	v_lshl_add_u64 v[130:131], s[16:17], 0, v[146:147]
	s_add_i32 m0, s47, 0x2000
	s_nop 0
	global_load_lds_dwordx4 v[130:131], off
	s_waitcnt vmcnt(6)
	s_barrier
	s_setprio 1
	v_mfma_f32_16x16x32_bf16 v[54:57], v[188:191], v[156:159], v[54:57]
	v_mfma_f32_16x16x32_bf16 v[44:47], v[208:211], v[156:159], v[44:47]
	v_mfma_f32_16x16x32_bf16 v[36:39], v[188:191], v[164:167], v[36:39]
	v_mfma_f32_16x16x32_bf16 v[28:31], v[208:211], v[164:167], v[28:31]
	v_mfma_f32_16x16x32_bf16 v[20:23], v[188:191], v[172:175], v[20:23]
	v_mfma_f32_16x16x32_bf16 v[12:15], v[208:211], v[172:175], v[12:15]
	v_mfma_f32_16x16x32_bf16 v[4:7], v[188:191], v[180:183], v[4:7]
	v_mfma_f32_16x16x32_bf16 v[0:3], v[208:211], v[180:183], v[0:3]
	v_mfma_f32_16x16x32_bf16 v[54:57], v[198:201], v[160:163], v[54:57]
	v_mfma_f32_16x16x32_bf16 v[44:47], v[212:215], v[160:163], v[44:47]
	v_mfma_f32_16x16x32_bf16 v[36:39], v[198:201], v[168:171], v[36:39]
	v_mfma_f32_16x16x32_bf16 v[28:31], v[212:215], v[168:171], v[28:31]
	v_mfma_f32_16x16x32_bf16 v[20:23], v[198:201], v[176:179], v[20:23]
	v_mfma_f32_16x16x32_bf16 v[12:15], v[212:215], v[176:179], v[12:15]
	v_mfma_f32_16x16x32_bf16 v[4:7], v[198:201], v[184:187], v[4:7]
	v_mfma_f32_16x16x32_bf16 v[0:3], v[212:215], v[184:187], v[0:3]
	s_setprio 0
	s_add_i32 s47, 0, 0x18000
	v_add_u32_e32 v142, s47, v204
	s_barrier
	ds_read_b128 v[130:133], v142
	ds_read_b128 v[134:137], v142 offset:1024
	ds_read_b128 v[138:141], v142 offset:2048
	ds_read_b128 v[142:145], v142 offset:3072
	s_add_u32 s16, s22, 0xb0000
	s_addc_u32 s17, s23, 0
	s_mov_b32 m0, s35
	v_lshl_add_u64 v[188:189], s[16:17], 0, v[48:49]
	ds_read_b128 v[156:159], v206 offset:32768
	ds_read_b128 v[160:163], v206 offset:33792
	ds_read_b128 v[164:167], v206 offset:34816
	ds_read_b128 v[168:171], v206 offset:35840
	ds_read_b128 v[172:175], v206 offset:36864
	ds_read_b128 v[176:179], v206 offset:37888
	ds_read_b128 v[180:183], v206 offset:38912
	ds_read_b128 v[184:187], v206 offset:39936
	global_load_lds_dwordx4 v[188:189], off
	v_lshl_add_u64 v[188:189], s[16:17], 0, v[146:147]
	s_mov_b32 m0, s36
	s_nop 0
	global_load_lds_dwordx4 v[188:189], off
	s_waitcnt lgkmcnt(8)
	s_barrier
	s_waitcnt lgkmcnt(0)
	s_setprio 1
	s_waitcnt lgkmcnt(0)
	v_mfma_f32_16x16x32_bf16 v[126:129], v[130:133], v[156:159], v[126:129]
	v_mfma_f32_16x16x32_bf16 v[122:125], v[138:141], v[156:159], v[122:125]
	v_mfma_f32_16x16x32_bf16 v[114:117], v[130:133], v[164:167], v[114:117]
	v_mfma_f32_16x16x32_bf16 v[106:109], v[138:141], v[164:167], v[106:109]
	v_mfma_f32_16x16x32_bf16 v[98:101], v[130:133], v[172:175], v[98:101]
	v_mfma_f32_16x16x32_bf16 v[90:93], v[138:141], v[172:175], v[90:93]
	v_mfma_f32_16x16x32_bf16 v[82:85], v[130:133], v[180:183], v[82:85]
	v_mfma_f32_16x16x32_bf16 v[74:77], v[138:141], v[180:183], v[74:77]
	v_mfma_f32_16x16x32_bf16 v[126:129], v[134:137], v[160:163], v[126:129]
	v_mfma_f32_16x16x32_bf16 v[122:125], v[142:145], v[160:163], v[122:125]
	v_mfma_f32_16x16x32_bf16 v[114:117], v[134:137], v[168:171], v[114:117]
	v_mfma_f32_16x16x32_bf16 v[106:109], v[142:145], v[168:171], v[106:109]
	v_mfma_f32_16x16x32_bf16 v[98:101], v[134:137], v[176:179], v[98:101]
	v_mfma_f32_16x16x32_bf16 v[90:93], v[142:145], v[176:179], v[90:93]
	v_mfma_f32_16x16x32_bf16 v[82:85], v[134:137], v[184:187], v[82:85]
	v_mfma_f32_16x16x32_bf16 v[74:77], v[142:145], v[184:187], v[74:77]
	s_setprio 0
	s_barrier
	s_add_i32 s22, 0, 0x1c000
	s_add_i32 s16, s47, s25
	v_add_u32_e32 v207, s22, v204
	v_lshl_add_u64 v[192:193], v[192:193], 0, s[66:67]
	s_mov_b32 m0, s16
	ds_read_b128 v[188:191], v207
	ds_read_b128 v[198:201], v207 offset:1024
	ds_read_b128 v[208:211], v207 offset:2048
	ds_read_b128 v[212:215], v207 offset:3072
	global_load_lds_dwordx4 v[192:193], off
	v_lshl_add_u64 v[192:193], v[202:203], 0, s[66:67]
	s_add_i32 m0, s16, 0x2000
	s_nop 0
	global_load_lds_dwordx4 v[192:193], off
	s_barrier
	s_waitcnt lgkmcnt(0)
	s_setprio 1
	s_waitcnt lgkmcnt(0)
	v_mfma_f32_16x16x32_bf16 v[118:121], v[188:191], v[156:159], v[118:121]
	v_mfma_f32_16x16x32_bf16 v[110:113], v[208:211], v[156:159], v[110:113]
	v_mfma_f32_16x16x32_bf16 v[102:105], v[188:191], v[164:167], v[102:105]
	v_mfma_f32_16x16x32_bf16 v[94:97], v[208:211], v[164:167], v[94:97]
	v_mfma_f32_16x16x32_bf16 v[86:89], v[188:191], v[172:175], v[86:89]
	v_mfma_f32_16x16x32_bf16 v[78:81], v[208:211], v[172:175], v[78:81]
	v_mfma_f32_16x16x32_bf16 v[70:73], v[188:191], v[180:183], v[70:73]
	v_mfma_f32_16x16x32_bf16 v[66:69], v[208:211], v[180:183], v[66:69]
	v_mfma_f32_16x16x32_bf16 v[118:121], v[198:201], v[160:163], v[118:121]
	v_mfma_f32_16x16x32_bf16 v[110:113], v[212:215], v[160:163], v[110:113]
	v_mfma_f32_16x16x32_bf16 v[102:105], v[198:201], v[168:171], v[102:105]
	v_mfma_f32_16x16x32_bf16 v[94:97], v[212:215], v[168:171], v[94:97]
	v_mfma_f32_16x16x32_bf16 v[86:89], v[198:201], v[176:179], v[86:89]
	v_mfma_f32_16x16x32_bf16 v[78:81], v[212:215], v[176:179], v[78:81]
	v_mfma_f32_16x16x32_bf16 v[70:73], v[198:201], v[184:187], v[70:73]
	v_mfma_f32_16x16x32_bf16 v[66:69], v[212:215], v[184:187], v[66:69]
	s_setprio 0
	s_mov_b32 m0, s39
	v_lshl_add_u64 v[192:193], v[216:217], 0, s[66:67]
	s_barrier
	ds_read_b128 v[156:159], v206 offset:49152
	ds_read_b128 v[160:163], v206 offset:50176
	ds_read_b128 v[164:167], v206 offset:51200
	ds_read_b128 v[168:171], v206 offset:52224
	ds_read_b128 v[172:175], v206 offset:53248
	ds_read_b128 v[176:179], v206 offset:54272
	ds_read_b128 v[180:183], v206 offset:55296
	ds_read_b128 v[184:187], v206 offset:56320
	global_load_lds_dwordx4 v[192:193], off
	v_lshl_add_u64 v[192:193], v[218:219], 0, s[66:67]
	s_mov_b32 m0, s40
	s_nop 0
	global_load_lds_dwordx4 v[192:193], off
	s_barrier
	s_waitcnt lgkmcnt(0)
	s_setprio 1
	s_waitcnt lgkmcnt(0)
	v_mfma_f32_16x16x32_bf16 v[62:65], v[130:133], v[156:159], v[62:65]
	v_mfma_f32_16x16x32_bf16 v[58:61], v[138:141], v[156:159], v[58:61]
	v_mfma_f32_16x16x32_bf16 v[50:53], v[130:133], v[164:167], v[50:53]
	v_mfma_f32_16x16x32_bf16 v[40:43], v[138:141], v[164:167], v[40:43]
	v_mfma_f32_16x16x32_bf16 v[32:35], v[130:133], v[172:175], v[32:35]
	v_mfma_f32_16x16x32_bf16 v[24:27], v[138:141], v[172:175], v[24:27]
	v_mfma_f32_16x16x32_bf16 v[16:19], v[130:133], v[180:183], v[16:19]
	v_mfma_f32_16x16x32_bf16 v[8:11], v[138:141], v[180:183], v[8:11]
	v_mfma_f32_16x16x32_bf16 v[62:65], v[134:137], v[160:163], v[62:65]
	v_mfma_f32_16x16x32_bf16 v[58:61], v[142:145], v[160:163], v[58:61]
	v_mfma_f32_16x16x32_bf16 v[50:53], v[134:137], v[168:171], v[50:53]
	v_mfma_f32_16x16x32_bf16 v[40:43], v[142:145], v[168:171], v[40:43]
	v_mfma_f32_16x16x32_bf16 v[32:35], v[134:137], v[176:179], v[32:35]
	v_mfma_f32_16x16x32_bf16 v[24:27], v[142:145], v[176:179], v[24:27]
	v_mfma_f32_16x16x32_bf16 v[16:19], v[134:137], v[184:187], v[16:19]
	v_mfma_f32_16x16x32_bf16 v[8:11], v[142:145], v[184:187], v[8:11]
	s_setprio 0
	s_barrier
	s_add_u32 s16, s20, 0xb0080
	s_addc_u32 s17, s21, 0
	s_add_i32 s20, s22, s25
	v_lshl_add_u64 v[130:131], s[16:17], 0, v[48:49]
	s_mov_b32 m0, s20
	s_nop 0
	global_load_lds_dwordx4 v[130:131], off
	v_lshl_add_u64 v[130:131], s[16:17], 0, v[146:147]
	s_add_i32 m0, s20, 0x2000
	s_nop 0
	global_load_lds_dwordx4 v[130:131], off
	s_waitcnt vmcnt(6)
	s_barrier
	s_setprio 1
	v_mfma_f32_16x16x32_bf16 v[54:57], v[188:191], v[156:159], v[54:57]
	v_mfma_f32_16x16x32_bf16 v[44:47], v[208:211], v[156:159], v[44:47]
	v_mfma_f32_16x16x32_bf16 v[36:39], v[188:191], v[164:167], v[36:39]
	v_mfma_f32_16x16x32_bf16 v[28:31], v[208:211], v[164:167], v[28:31]
	v_mfma_f32_16x16x32_bf16 v[20:23], v[188:191], v[172:175], v[20:23]
	v_mfma_f32_16x16x32_bf16 v[12:15], v[208:211], v[172:175], v[12:15]
	v_mfma_f32_16x16x32_bf16 v[4:7], v[188:191], v[180:183], v[4:7]
	v_mfma_f32_16x16x32_bf16 v[0:3], v[208:211], v[180:183], v[0:3]
	v_mfma_f32_16x16x32_bf16 v[54:57], v[198:201], v[160:163], v[54:57]
	v_mfma_f32_16x16x32_bf16 v[44:47], v[212:215], v[160:163], v[44:47]
	v_mfma_f32_16x16x32_bf16 v[36:39], v[198:201], v[168:171], v[36:39]
	v_mfma_f32_16x16x32_bf16 v[28:31], v[212:215], v[168:171], v[28:31]
	v_mfma_f32_16x16x32_bf16 v[20:23], v[198:201], v[176:179], v[20:23]
	v_mfma_f32_16x16x32_bf16 v[12:15], v[212:215], v[176:179], v[12:15]
	v_mfma_f32_16x16x32_bf16 v[4:7], v[198:201], v[184:187], v[4:7]
	v_mfma_f32_16x16x32_bf16 v[0:3], v[212:215], v[184:187], v[0:3]
	s_setprio 0
	s_add_i32 s46, s46, 2
	s_add_u32 s44, s44, 0x100
	s_addc_u32 s45, s45, 0
	s_cmp_gt_u32 s46, 41
	s_mov_b64 s[16:17], s[18:19]
	s_barrier
	s_cbranch_scc0 .LBB0_1421
	s_mul_hi_i32 s16, s14, 0x38e38e39
	s_lshr_b32 s17, s16, 31
	s_ashr_i32 s16, s16, 1
	s_add_i32 s16, s16, s17
	s_mul_i32 s17, s16, -9
	v_lshl_or_b32 v156, s15, 8, v205
	s_ashr_i32 s15, s14, 31
	s_add_i32 s18, s17, s14
	s_lshl_b64 s[14:15], s[14:15], 19
	s_ashr_i32 s17, s16, 31
	v_lshl_add_u64 v[158:159], v[150:151], 0, s[14:15]
	v_sub_co_u32_e64 v130, s[14:15], s18, 1
	s_lshl_b64 s[18:19], s[16:17], 23
	s_and_b64 s[14:15], s[14:15], exec
	v_ashrrev_i32_e32 v131, 31, v130
	s_cselect_b32 s14, 32, s16
	v_lshlrev_b64 v[130:131], 20, v[130:131]
	s_mul_hi_i32 s15, s14, 0x6000
	s_mulk_i32 s14, 0x6000
	v_ashrrev_i32_e32 v157, 31, v156
	v_lshl_add_u64 v[130:131], s[6:7], 0, v[130:131]
	s_add_u32 s14, s37, s14
	v_lshl_add_u64 v[130:131], v[130:131], 0, s[18:19]
	s_addc_u32 s15, s38, s15
	v_lshlrev_b64 v[208:209], 2, v[156:157]
	v_lshl_add_u64 v[162:163], v[130:131], 0, v[148:149]
	v_lshl_add_u64 v[130:131], s[14:15], 0, v[208:209]
	v_lshl_add_u64 v[156:157], v[156:157], 1, v[158:159]
	global_load_dwordx4 v[142:145], v[130:131], off
	global_load_dwordx4 v[138:141], v[130:131], off offset:64
	global_load_dwordx4 v[134:137], v[130:131], off offset:512
	s_nop 0
	global_load_dwordx4 v[130:133], v[130:131], off offset:576
	s_nop 0
	s_mov_b32 s14, 0x40000
	s_nop 0
	v_lshl_add_u64 v[162:163], v[162:163], 0, v[208:209]
	s_nop 0
	s_mov_b32 s15, s42
	s_nop 0
	s_mov_b32 s14, 0x48000
	s_nop 0
	s_mov_b32 s14, 0x50000
	s_nop 0
	s_mov_b32 s14, 0x58000
	s_nop 0
	s_mov_b32 s14, 0x20000
	s_nop 0
	s_nop 0
	s_mov_b64 s[18:19], s[12:13]
	s_mov_b64 s[16:17], s[10:11]
	v_and_b32_e32 v202, 16, v224
	v_lshrrev_b32_e32 v203, 1, v202
	v_add_u32_e32 v202, v202, v203
	v_mov_b32_e32 v203, 0
	v_mov_b32_e32 v223, 0
	v_lshl_add_u64 v[246:247], v[156:157], 0, v[202:203]
	v_mov_b32_e32 v222, 0x0
	v_lshl_add_u64 v[190:191], v[246:247], 0, v[222:223]
	global_load_dwordx4 v[198:201], v[190:191], off
	global_load_dwordx4 v[218:221], v[190:191], off offset:256
	v_mov_b32_e32 v222, 0x8000
	v_lshl_add_u64 v[190:191], v[246:247], 0, v[222:223]
	global_load_dwordx4 v[242:245], v[190:191], off
	global_load_dwordx4 v[164:167], v[190:191], off offset:256
	v_mov_b32_e32 v222, 0x10000
	v_lshl_add_u64 v[190:191], v[246:247], 0, v[222:223]
	global_load_dwordx4 v[168:171], v[190:191], off
	global_load_dwordx4 v[172:175], v[190:191], off offset:256
	v_mov_b32_e32 v222, 0x18000
	v_lshl_add_u64 v[190:191], v[246:247], 0, v[222:223]
	global_load_dwordx4 v[176:179], v[190:191], off
	global_load_dwordx4 v[180:183], v[190:191], off offset:256
	v_mov_b32_e32 v222, 0x40000
	v_lshl_add_u64 v[190:191], v[246:247], 0, v[222:223]
	global_load_dwordx4 v[184:187], v[190:191], off
	s_waitcnt vmcnt(8)
	v_permlane16_swap_b32 v198, v200
	v_permlane16_swap_b32 v199, v201
	s_nop 1
	v_lshlrev_b32_e32 v210, 16, v198
	v_and_b32_e32 v211, 0xffff0000, v198
	v_lshlrev_b32_e32 v212, 16, v199
	v_and_b32_e32 v213, 0xffff0000, v199
	v_pk_fma_f32 v[126:127], v[126:127], v[142:143], v[210:211]
	v_pk_fma_f32 v[128:129], v[128:129], v[144:145], v[212:213]
	v_lshlrev_b32_e32 v214, 16, v200
	v_and_b32_e32 v215, 0xffff0000, v200
	v_lshlrev_b32_e32 v216, 16, v201
	v_and_b32_e32 v217, 0xffff0000, v201
	v_pk_fma_f32 v[122:123], v[122:123], v[138:139], v[214:215]
	v_pk_fma_f32 v[124:125], v[124:125], v[140:141], v[216:217]
	v_mov_b32_e32 v222, 0x0
	v_lshl_add_u64 v[192:193], v[162:163], 0, v[222:223]
	global_store_dwordx4 v[192:193], v[126:129], off
	global_store_dwordx4 v[192:193], v[122:125], off offset:64
	global_load_dwordx4 v[198:201], v[190:191], off offset:256
	s_waitcnt vmcnt(10)
	v_permlane16_swap_b32 v218, v220
	v_permlane16_swap_b32 v219, v221
	s_nop 1
	v_lshlrev_b32_e32 v210, 16, v218
	v_and_b32_e32 v211, 0xffff0000, v218
	v_lshlrev_b32_e32 v212, 16, v219
	v_and_b32_e32 v213, 0xffff0000, v219
	v_pk_fma_f32 v[118:119], v[118:119], v[134:135], v[210:211]
	v_pk_fma_f32 v[120:121], v[120:121], v[136:137], v[212:213]
	v_lshlrev_b32_e32 v214, 16, v220
	v_and_b32_e32 v215, 0xffff0000, v220
	v_lshlrev_b32_e32 v216, 16, v221
	v_and_b32_e32 v217, 0xffff0000, v221
	v_pk_fma_f32 v[110:111], v[110:111], v[130:131], v[214:215]
	v_pk_fma_f32 v[112:113], v[112:113], v[132:133], v[216:217]
	v_mov_b32_e32 v222, 0x0
	v_lshl_add_u64 v[192:193], v[162:163], 0, v[222:223]
	global_store_dwordx4 v[192:193], v[118:121], off offset:512
	global_store_dwordx4 v[192:193], v[110:113], off offset:576
	v_mov_b32_e32 v222, 0x48000
	v_lshl_add_u64 v[190:191], v[246:247], 0, v[222:223]
	global_load_dwordx4 v[218:221], v[190:191], off
	s_waitcnt vmcnt(12)
	v_permlane16_swap_b32 v242, v244
	v_permlane16_swap_b32 v243, v245
	s_nop 1
	v_lshlrev_b32_e32 v210, 16, v242
	v_and_b32_e32 v211, 0xffff0000, v242
	v_lshlrev_b32_e32 v212, 16, v243
	v_and_b32_e32 v213, 0xffff0000, v243
	v_pk_fma_f32 v[114:115], v[114:115], v[142:143], v[210:211]
	v_pk_fma_f32 v[116:117], v[116:117], v[144:145], v[212:213]
	v_lshlrev_b32_e32 v214, 16, v244
	v_and_b32_e32 v215, 0xffff0000, v244
	v_lshlrev_b32_e32 v216, 16, v245
	v_and_b32_e32 v217, 0xffff0000, v245
	v_pk_fma_f32 v[106:107], v[106:107], v[138:139], v[214:215]
	v_pk_fma_f32 v[108:109], v[108:109], v[140:141], v[216:217]
	v_mov_b32_e32 v222, 0x10000
	v_lshl_add_u64 v[192:193], v[162:163], 0, v[222:223]
	global_store_dwordx4 v[192:193], v[114:117], off
	global_store_dwordx4 v[192:193], v[106:109], off offset:64
	global_load_dwordx4 v[242:245], v[190:191], off offset:256
	s_waitcnt vmcnt(14)
	v_permlane16_swap_b32 v164, v166
	v_permlane16_swap_b32 v165, v167
	s_nop 1
	v_lshlrev_b32_e32 v210, 16, v164
	v_and_b32_e32 v211, 0xffff0000, v164
	v_lshlrev_b32_e32 v212, 16, v165
	v_and_b32_e32 v213, 0xffff0000, v165
	v_pk_fma_f32 v[102:103], v[102:103], v[134:135], v[210:211]
	v_pk_fma_f32 v[104:105], v[104:105], v[136:137], v[212:213]
	v_lshlrev_b32_e32 v214, 16, v166
	v_and_b32_e32 v215, 0xffff0000, v166
	v_lshlrev_b32_e32 v216, 16, v167
	v_and_b32_e32 v217, 0xffff0000, v167
	v_pk_fma_f32 v[94:95], v[94:95], v[130:131], v[214:215]
	v_pk_fma_f32 v[96:97], v[96:97], v[132:133], v[216:217]
	v_mov_b32_e32 v222, 0x10000
	v_lshl_add_u64 v[192:193], v[162:163], 0, v[222:223]
	global_store_dwordx4 v[192:193], v[102:105], off offset:512
	global_store_dwordx4 v[192:193], v[94:97], off offset:576
	v_mov_b32_e32 v222, 0x50000
	v_lshl_add_u64 v[190:191], v[246:247], 0, v[222:223]
	global_load_dwordx4 v[164:167], v[190:191], off
	s_waitcnt vmcnt(16)
	v_permlane16_swap_b32 v168, v170
	v_permlane16_swap_b32 v169, v171
	s_nop 1
	v_lshlrev_b32_e32 v210, 16, v168
	v_and_b32_e32 v211, 0xffff0000, v168
	v_lshlrev_b32_e32 v212, 16, v169
	v_and_b32_e32 v213, 0xffff0000, v169
	v_pk_fma_f32 v[98:99], v[98:99], v[142:143], v[210:211]
	v_pk_fma_f32 v[100:101], v[100:101], v[144:145], v[212:213]
	v_lshlrev_b32_e32 v214, 16, v170
	v_and_b32_e32 v215, 0xffff0000, v170
	v_lshlrev_b32_e32 v216, 16, v171
	v_and_b32_e32 v217, 0xffff0000, v171
	v_pk_fma_f32 v[90:91], v[90:91], v[138:139], v[214:215]
	v_pk_fma_f32 v[92:93], v[92:93], v[140:141], v[216:217]
	v_mov_b32_e32 v222, 0x20000
	v_lshl_add_u64 v[192:193], v[162:163], 0, v[222:223]
	global_store_dwordx4 v[192:193], v[98:101], off
	global_store_dwordx4 v[192:193], v[90:93], off offset:64
	global_load_dwordx4 v[168:171], v[190:191], off offset:256
	s_waitcnt vmcnt(18)
	v_permlane16_swap_b32 v172, v174
	v_permlane16_swap_b32 v173, v175
	s_nop 1
	v_lshlrev_b32_e32 v210, 16, v172
	v_and_b32_e32 v211, 0xffff0000, v172
	v_lshlrev_b32_e32 v212, 16, v173
	v_and_b32_e32 v213, 0xffff0000, v173
	v_pk_fma_f32 v[86:87], v[86:87], v[134:135], v[210:211]
	v_pk_fma_f32 v[88:89], v[88:89], v[136:137], v[212:213]
	v_lshlrev_b32_e32 v214, 16, v174
	v_and_b32_e32 v215, 0xffff0000, v174
	v_lshlrev_b32_e32 v216, 16, v175
	v_and_b32_e32 v217, 0xffff0000, v175
	v_pk_fma_f32 v[78:79], v[78:79], v[130:131], v[214:215]
	v_pk_fma_f32 v[80:81], v[80:81], v[132:133], v[216:217]
	v_mov_b32_e32 v222, 0x20000
	v_lshl_add_u64 v[192:193], v[162:163], 0, v[222:223]
	global_store_dwordx4 v[192:193], v[86:89], off offset:512
	global_store_dwordx4 v[192:193], v[78:81], off offset:576
	v_mov_b32_e32 v222, 0x58000
	v_lshl_add_u64 v[190:191], v[246:247], 0, v[222:223]
	global_load_dwordx4 v[172:175], v[190:191], off
	s_waitcnt vmcnt(20)
	v_permlane16_swap_b32 v176, v178
	v_permlane16_swap_b32 v177, v179
	s_nop 1
	v_lshlrev_b32_e32 v210, 16, v176
	v_and_b32_e32 v211, 0xffff0000, v176
	v_lshlrev_b32_e32 v212, 16, v177
	v_and_b32_e32 v213, 0xffff0000, v177
	v_pk_fma_f32 v[82:83], v[82:83], v[142:143], v[210:211]
	v_pk_fma_f32 v[84:85], v[84:85], v[144:145], v[212:213]
	v_lshlrev_b32_e32 v214, 16, v178
	v_and_b32_e32 v215, 0xffff0000, v178
	v_lshlrev_b32_e32 v216, 16, v179
	v_and_b32_e32 v217, 0xffff0000, v179
	v_pk_fma_f32 v[74:75], v[74:75], v[138:139], v[214:215]
	v_pk_fma_f32 v[76:77], v[76:77], v[140:141], v[216:217]
	v_mov_b32_e32 v222, 0x30000
	v_lshl_add_u64 v[192:193], v[162:163], 0, v[222:223]
	global_store_dwordx4 v[192:193], v[82:85], off
	global_store_dwordx4 v[192:193], v[74:77], off offset:64
	global_load_dwordx4 v[176:179], v[190:191], off offset:256
	s_waitcnt vmcnt(22)
	v_permlane16_swap_b32 v180, v182
	v_permlane16_swap_b32 v181, v183
	s_nop 1
	v_lshlrev_b32_e32 v210, 16, v180
	v_and_b32_e32 v211, 0xffff0000, v180
	v_lshlrev_b32_e32 v212, 16, v181
	v_and_b32_e32 v213, 0xffff0000, v181
	v_pk_fma_f32 v[70:71], v[70:71], v[134:135], v[210:211]
	v_pk_fma_f32 v[72:73], v[72:73], v[136:137], v[212:213]
	v_lshlrev_b32_e32 v214, 16, v182
	v_and_b32_e32 v215, 0xffff0000, v182
	v_lshlrev_b32_e32 v216, 16, v183
	v_and_b32_e32 v217, 0xffff0000, v183
	v_pk_fma_f32 v[66:67], v[66:67], v[130:131], v[214:215]
	v_pk_fma_f32 v[68:69], v[68:69], v[132:133], v[216:217]
	v_mov_b32_e32 v222, 0x30000
	v_lshl_add_u64 v[192:193], v[162:163], 0, v[222:223]
	global_store_dwordx4 v[192:193], v[70:73], off offset:512
	global_store_dwordx4 v[192:193], v[66:69], off offset:576
	s_waitcnt vmcnt(23)
	v_permlane16_swap_b32 v184, v186
	v_permlane16_swap_b32 v185, v187
	s_nop 1
	v_lshlrev_b32_e32 v210, 16, v184
	v_and_b32_e32 v211, 0xffff0000, v184
	v_lshlrev_b32_e32 v212, 16, v185
	v_and_b32_e32 v213, 0xffff0000, v185
	v_pk_fma_f32 v[62:63], v[62:63], v[142:143], v[210:211]
	v_pk_fma_f32 v[64:65], v[64:65], v[144:145], v[212:213]
	v_lshlrev_b32_e32 v214, 16, v186
	v_and_b32_e32 v215, 0xffff0000, v186
	v_lshlrev_b32_e32 v216, 16, v187
	v_and_b32_e32 v217, 0xffff0000, v187
	v_pk_fma_f32 v[58:59], v[58:59], v[138:139], v[214:215]
	v_pk_fma_f32 v[60:61], v[60:61], v[140:141], v[216:217]
	v_mov_b32_e32 v222, 0x80000
	v_lshl_add_u64 v[192:193], v[162:163], 0, v[222:223]
	global_store_dwordx4 v[192:193], v[62:65], off
	global_store_dwordx4 v[192:193], v[58:61], off offset:64
	s_waitcnt vmcnt(22)
	v_permlane16_swap_b32 v198, v200
	v_permlane16_swap_b32 v199, v201
	s_nop 1
	v_lshlrev_b32_e32 v210, 16, v198
	v_and_b32_e32 v211, 0xffff0000, v198
	v_lshlrev_b32_e32 v212, 16, v199
	v_and_b32_e32 v213, 0xffff0000, v199
	v_pk_fma_f32 v[54:55], v[54:55], v[134:135], v[210:211]
	v_pk_fma_f32 v[56:57], v[56:57], v[136:137], v[212:213]
	v_lshlrev_b32_e32 v214, 16, v200
	v_and_b32_e32 v215, 0xffff0000, v200
	v_lshlrev_b32_e32 v216, 16, v201
	v_and_b32_e32 v217, 0xffff0000, v201
	v_pk_fma_f32 v[44:45], v[44:45], v[130:131], v[214:215]
	v_pk_fma_f32 v[46:47], v[46:47], v[132:133], v[216:217]
	v_mov_b32_e32 v222, 0x80000
	v_lshl_add_u64 v[192:193], v[162:163], 0, v[222:223]
	global_store_dwordx4 v[192:193], v[54:57], off offset:512
	global_store_dwordx4 v[192:193], v[44:47], off offset:576
	s_waitcnt vmcnt(21)
	v_permlane16_swap_b32 v218, v220
	v_permlane16_swap_b32 v219, v221
	s_nop 1
	v_lshlrev_b32_e32 v210, 16, v218
	v_and_b32_e32 v211, 0xffff0000, v218
	v_lshlrev_b32_e32 v212, 16, v219
	v_and_b32_e32 v213, 0xffff0000, v219
	v_pk_fma_f32 v[50:51], v[50:51], v[142:143], v[210:211]
	v_pk_fma_f32 v[52:53], v[52:53], v[144:145], v[212:213]
	v_lshlrev_b32_e32 v214, 16, v220
	v_and_b32_e32 v215, 0xffff0000, v220
	v_lshlrev_b32_e32 v216, 16, v221
	v_and_b32_e32 v217, 0xffff0000, v221
	v_pk_fma_f32 v[40:41], v[40:41], v[138:139], v[214:215]
	v_pk_fma_f32 v[42:43], v[42:43], v[140:141], v[216:217]
	v_mov_b32_e32 v222, 0x90000
	v_lshl_add_u64 v[192:193], v[162:163], 0, v[222:223]
	global_store_dwordx4 v[192:193], v[50:53], off
	global_store_dwordx4 v[192:193], v[40:43], off offset:64
	s_waitcnt vmcnt(20)
	v_permlane16_swap_b32 v242, v244
	v_permlane16_swap_b32 v243, v245
	s_nop 1
	v_lshlrev_b32_e32 v210, 16, v242
	v_and_b32_e32 v211, 0xffff0000, v242
	v_lshlrev_b32_e32 v212, 16, v243
	v_and_b32_e32 v213, 0xffff0000, v243
	v_pk_fma_f32 v[36:37], v[36:37], v[134:135], v[210:211]
	v_pk_fma_f32 v[38:39], v[38:39], v[136:137], v[212:213]
	v_lshlrev_b32_e32 v214, 16, v244
	v_and_b32_e32 v215, 0xffff0000, v244
	v_lshlrev_b32_e32 v216, 16, v245
	v_and_b32_e32 v217, 0xffff0000, v245
	v_pk_fma_f32 v[28:29], v[28:29], v[130:131], v[214:215]
	v_pk_fma_f32 v[30:31], v[30:31], v[132:133], v[216:217]
	v_mov_b32_e32 v222, 0x90000
	v_lshl_add_u64 v[192:193], v[162:163], 0, v[222:223]
	global_store_dwordx4 v[192:193], v[36:39], off offset:512
	global_store_dwordx4 v[192:193], v[28:31], off offset:576
	s_waitcnt vmcnt(19)
	v_permlane16_swap_b32 v164, v166
	v_permlane16_swap_b32 v165, v167
	s_nop 1
	v_lshlrev_b32_e32 v210, 16, v164
	v_and_b32_e32 v211, 0xffff0000, v164
	v_lshlrev_b32_e32 v212, 16, v165
	v_and_b32_e32 v213, 0xffff0000, v165
	v_pk_fma_f32 v[32:33], v[32:33], v[142:143], v[210:211]
	v_pk_fma_f32 v[34:35], v[34:35], v[144:145], v[212:213]
	v_lshlrev_b32_e32 v214, 16, v166
	v_and_b32_e32 v215, 0xffff0000, v166
	v_lshlrev_b32_e32 v216, 16, v167
	v_and_b32_e32 v217, 0xffff0000, v167
	v_pk_fma_f32 v[24:25], v[24:25], v[138:139], v[214:215]
	v_pk_fma_f32 v[26:27], v[26:27], v[140:141], v[216:217]
	v_mov_b32_e32 v222, 0xa0000
	v_lshl_add_u64 v[192:193], v[162:163], 0, v[222:223]
	global_store_dwordx4 v[192:193], v[32:35], off
	global_store_dwordx4 v[192:193], v[24:27], off offset:64
	s_waitcnt vmcnt(18)
	v_permlane16_swap_b32 v168, v170
	v_permlane16_swap_b32 v169, v171
	s_nop 1
	v_lshlrev_b32_e32 v210, 16, v168
	v_and_b32_e32 v211, 0xffff0000, v168
	v_lshlrev_b32_e32 v212, 16, v169
	v_and_b32_e32 v213, 0xffff0000, v169
	v_pk_fma_f32 v[20:21], v[20:21], v[134:135], v[210:211]
	v_pk_fma_f32 v[22:23], v[22:23], v[136:137], v[212:213]
	v_lshlrev_b32_e32 v214, 16, v170
	v_and_b32_e32 v215, 0xffff0000, v170
	v_lshlrev_b32_e32 v216, 16, v171
	v_and_b32_e32 v217, 0xffff0000, v171
	v_pk_fma_f32 v[12:13], v[12:13], v[130:131], v[214:215]
	v_pk_fma_f32 v[14:15], v[14:15], v[132:133], v[216:217]
	v_mov_b32_e32 v222, 0xa0000
	v_lshl_add_u64 v[192:193], v[162:163], 0, v[222:223]
	global_store_dwordx4 v[192:193], v[20:23], off offset:512
	global_store_dwordx4 v[192:193], v[12:15], off offset:576
	s_waitcnt vmcnt(17)
	v_permlane16_swap_b32 v172, v174
	v_permlane16_swap_b32 v173, v175
	s_nop 1
	v_lshlrev_b32_e32 v210, 16, v172
	v_and_b32_e32 v211, 0xffff0000, v172
	v_lshlrev_b32_e32 v212, 16, v173
	v_and_b32_e32 v213, 0xffff0000, v173
	v_pk_fma_f32 v[16:17], v[16:17], v[142:143], v[210:211]
	v_pk_fma_f32 v[18:19], v[18:19], v[144:145], v[212:213]
	v_lshlrev_b32_e32 v214, 16, v174
	v_and_b32_e32 v215, 0xffff0000, v174
	v_lshlrev_b32_e32 v216, 16, v175
	v_and_b32_e32 v217, 0xffff0000, v175
	v_pk_fma_f32 v[8:9], v[8:9], v[138:139], v[214:215]
	v_pk_fma_f32 v[10:11], v[10:11], v[140:141], v[216:217]
	v_mov_b32_e32 v222, 0xb0000
	v_lshl_add_u64 v[192:193], v[162:163], 0, v[222:223]
	global_store_dwordx4 v[192:193], v[16:19], off
	global_store_dwordx4 v[192:193], v[8:11], off offset:64
	s_waitcnt vmcnt(16)
	v_permlane16_swap_b32 v176, v178
	v_permlane16_swap_b32 v177, v179
	s_nop 1
	v_lshlrev_b32_e32 v210, 16, v176
	v_and_b32_e32 v211, 0xffff0000, v176
	v_lshlrev_b32_e32 v212, 16, v177
	v_and_b32_e32 v213, 0xffff0000, v177
	v_pk_fma_f32 v[4:5], v[4:5], v[134:135], v[210:211]
	v_pk_fma_f32 v[6:7], v[6:7], v[136:137], v[212:213]
	v_lshlrev_b32_e32 v214, 16, v178
	v_and_b32_e32 v215, 0xffff0000, v178
	v_lshlrev_b32_e32 v216, 16, v179
	v_and_b32_e32 v217, 0xffff0000, v179
	v_pk_fma_f32 v[0:1], v[0:1], v[130:131], v[214:215]
	v_pk_fma_f32 v[2:3], v[2:3], v[132:133], v[216:217]
	v_mov_b32_e32 v222, 0xb0000
	v_lshl_add_u64 v[192:193], v[162:163], 0, v[222:223]
	global_store_dwordx4 v[192:193], v[4:7], off offset:512
	global_store_dwordx4 v[192:193], v[0:3], off offset:576
	s_mov_b32 s14, 0x30000
	s_mov_b32 s14, 0x80000
	s_mov_b32 s14, 0x90000
	s_mov_b32 s14, 0xa0000
	s_mov_b32 s14, 0xb0000
	s_and_b64 vcc, exec, s[0:1]
	s_mov_b32 s14, s43
	s_cbranch_vccz .LBB0_1418
	s_waitcnt vmcnt(0)
	s_cmpk_gt_u32 s24, 0xff
	s_cbranch_scc1 .LBB0_1425
	s_barrier

.LBB0_1435:
	s_add_u32 s20, s18, 0x100
	s_addc_u32 s21, s19, 0
	s_add_i32 s47, 0, 0x10000
	v_add_u32_e32 v142, s47, v242
	ds_read_b128 v[130:133], v142
	ds_read_b128 v[134:137], v142 offset:1024
	ds_read_b128 v[138:141], v142 offset:2048
	ds_read_b128 v[142:145], v142 offset:3072
	s_cmp_eq_u32 s46, 40
	s_cselect_b32 s25, s13, s21
	s_cselect_b32 s24, s12, s20
	s_cselect_b32 s23, s15, s45
	s_cselect_b32 s22, s14, s44
	v_lshl_add_u64 v[186:187], s[18:19], 0, v[150:151]
	s_add_i32 m0, s31, 0xc000
	ds_read_b128 v[154:157], v244
	ds_read_b128 v[158:161], v244 offset:1024
	ds_read_b128 v[162:165], v244 offset:2048
	ds_read_b128 v[166:169], v244 offset:3072
	ds_read_b128 v[170:173], v244 offset:4096
	ds_read_b128 v[174:177], v244 offset:5120
	ds_read_b128 v[178:181], v244 offset:6144
	ds_read_b128 v[182:185], v244 offset:7168
	global_load_lds_dwordx4 v[186:187], off
	v_lshl_add_u64 v[186:187], s[18:19], 0, v[152:153]
	s_add_i32 m0, s31, 0xe000
	s_nop 0
	global_load_lds_dwordx4 v[186:187], off
	s_waitcnt lgkmcnt(8)
	s_barrier
	s_waitcnt lgkmcnt(0)
	s_setprio 1
	s_waitcnt lgkmcnt(0)
	v_mfma_f32_16x16x32_bf16 v[126:129], v[130:133], v[154:157], v[126:129]
	v_mfma_f32_16x16x32_bf16 v[122:125], v[138:141], v[154:157], v[122:125]
	v_mfma_f32_16x16x32_bf16 v[114:117], v[130:133], v[162:165], v[114:117]
	v_mfma_f32_16x16x32_bf16 v[106:109], v[138:141], v[162:165], v[106:109]
	v_mfma_f32_16x16x32_bf16 v[98:101], v[130:133], v[170:173], v[98:101]
	v_mfma_f32_16x16x32_bf16 v[90:93], v[138:141], v[170:173], v[90:93]
	v_mfma_f32_16x16x32_bf16 v[82:85], v[130:133], v[178:181], v[82:85]
	v_mfma_f32_16x16x32_bf16 v[74:77], v[138:141], v[178:181], v[74:77]
	v_mfma_f32_16x16x32_bf16 v[126:129], v[134:137], v[158:161], v[126:129]
	v_mfma_f32_16x16x32_bf16 v[122:125], v[142:145], v[158:161], v[122:125]
	v_mfma_f32_16x16x32_bf16 v[114:117], v[134:137], v[166:169], v[114:117]
	v_mfma_f32_16x16x32_bf16 v[106:109], v[142:145], v[166:169], v[106:109]
	v_mfma_f32_16x16x32_bf16 v[98:101], v[134:137], v[174:177], v[98:101]
	v_mfma_f32_16x16x32_bf16 v[90:93], v[142:145], v[174:177], v[90:93]
	v_mfma_f32_16x16x32_bf16 v[82:85], v[134:137], v[182:185], v[82:85]
	v_mfma_f32_16x16x32_bf16 v[74:77], v[142:145], v[182:185], v[74:77]
	s_setprio 0
	s_barrier
	s_add_i32 s48, 0, 0x14000
	s_add_i32 s18, s47, s30
	v_add_u32_e32 v202, s48, v242
	v_lshl_add_u64 v[206:207], s[22:23], 0, v[48:49]
	s_mov_b32 m0, s18
	ds_read_b128 v[186:189], v202
	ds_read_b128 v[190:193], v202 offset:1024
	ds_read_b128 v[198:201], v202 offset:2048
	ds_read_b128 v[202:205], v202 offset:3072
	global_load_lds_dwordx4 v[206:207], off
	v_lshl_add_u64 v[208:209], s[22:23], 0, v[146:147]
	s_add_i32 m0, s18, 0x2000
	s_nop 0
	global_load_lds_dwordx4 v[208:209], off
	s_barrier
	s_waitcnt lgkmcnt(0)
	s_setprio 1
	s_waitcnt lgkmcnt(0)
	v_mfma_f32_16x16x32_bf16 v[118:121], v[186:189], v[154:157], v[118:121]
	v_mfma_f32_16x16x32_bf16 v[110:113], v[198:201], v[154:157], v[110:113]
	v_mfma_f32_16x16x32_bf16 v[102:105], v[186:189], v[162:165], v[102:105]
	v_mfma_f32_16x16x32_bf16 v[94:97], v[198:201], v[162:165], v[94:97]
	v_mfma_f32_16x16x32_bf16 v[86:89], v[186:189], v[170:173], v[86:89]
	v_mfma_f32_16x16x32_bf16 v[78:81], v[198:201], v[170:173], v[78:81]
	v_mfma_f32_16x16x32_bf16 v[70:73], v[186:189], v[178:181], v[70:73]
	v_mfma_f32_16x16x32_bf16 v[66:69], v[198:201], v[178:181], v[66:69]
	v_mfma_f32_16x16x32_bf16 v[118:121], v[190:193], v[158:161], v[118:121]
	v_mfma_f32_16x16x32_bf16 v[110:113], v[202:205], v[158:161], v[110:113]
	v_mfma_f32_16x16x32_bf16 v[102:105], v[190:193], v[166:169], v[102:105]
	v_mfma_f32_16x16x32_bf16 v[94:97], v[202:205], v[166:169], v[94:97]
	v_mfma_f32_16x16x32_bf16 v[86:89], v[190:193], v[174:177], v[86:89]
	v_mfma_f32_16x16x32_bf16 v[78:81], v[202:205], v[174:177], v[78:81]
	v_mfma_f32_16x16x32_bf16 v[70:73], v[190:193], v[182:185], v[70:73]
	v_mfma_f32_16x16x32_bf16 v[66:69], v[202:205], v[182:185], v[66:69]
	s_setprio 0
	s_mov_b32 m0, s31
	v_lshl_add_u64 v[210:211], s[24:25], 0, v[48:49]
	s_barrier
	ds_read_b128 v[154:157], v244 offset:16384
	ds_read_b128 v[158:161], v244 offset:17408
	ds_read_b128 v[162:165], v244 offset:18432
	ds_read_b128 v[166:169], v244 offset:19456
	ds_read_b128 v[170:173], v244 offset:20480
	ds_read_b128 v[174:177], v244 offset:21504
	ds_read_b128 v[178:181], v244 offset:22528
	ds_read_b128 v[182:185], v244 offset:23552
	global_load_lds_dwordx4 v[210:211], off
	v_lshl_add_u64 v[212:213], s[24:25], 0, v[146:147]
	s_mov_b32 m0, s34
	s_nop 0
	global_load_lds_dwordx4 v[212:213], off
	s_barrier
	s_waitcnt lgkmcnt(0)
	s_setprio 1
	s_waitcnt lgkmcnt(0)
	v_mfma_f32_16x16x32_bf16 v[62:65], v[130:133], v[154:157], v[62:65]
	v_mfma_f32_16x16x32_bf16 v[58:61], v[138:141], v[154:157], v[58:61]
	v_mfma_f32_16x16x32_bf16 v[50:53], v[130:133], v[162:165], v[50:53]
	v_mfma_f32_16x16x32_bf16 v[40:43], v[138:141], v[162:165], v[40:43]
	v_mfma_f32_16x16x32_bf16 v[32:35], v[130:133], v[170:173], v[32:35]
	v_mfma_f32_16x16x32_bf16 v[24:27], v[138:141], v[170:173], v[24:27]
	v_mfma_f32_16x16x32_bf16 v[16:19], v[130:133], v[178:181], v[16:19]
	v_mfma_f32_16x16x32_bf16 v[8:11], v[138:141], v[178:181], v[8:11]
	v_mfma_f32_16x16x32_bf16 v[62:65], v[134:137], v[158:161], v[62:65]
	v_mfma_f32_16x16x32_bf16 v[58:61], v[142:145], v[158:161], v[58:61]
	v_mfma_f32_16x16x32_bf16 v[50:53], v[134:137], v[166:169], v[50:53]
	v_mfma_f32_16x16x32_bf16 v[40:43], v[142:145], v[166:169], v[40:43]
	v_mfma_f32_16x16x32_bf16 v[32:35], v[134:137], v[174:177], v[32:35]
	v_mfma_f32_16x16x32_bf16 v[24:27], v[142:145], v[174:177], v[24:27]
	v_mfma_f32_16x16x32_bf16 v[16:19], v[134:137], v[182:185], v[16:19]
	v_mfma_f32_16x16x32_bf16 v[8:11], v[142:145], v[182:185], v[8:11]
	s_setprio 0
	s_barrier
	s_add_u32 s18, s22, 0xb0000
	s_addc_u32 s19, s23, 0
	s_add_i32 s47, s48, s30
	v_lshl_add_u64 v[130:131], s[18:19], 0, v[48:49]
	s_mov_b32 m0, s47
	s_nop 0
	global_load_lds_dwordx4 v[130:131], off
	v_lshl_add_u64 v[130:131], s[18:19], 0, v[146:147]
	s_add_i32 m0, s47, 0x2000
	s_nop 0
	global_load_lds_dwordx4 v[130:131], off
	s_waitcnt vmcnt(6)
	s_barrier
	s_setprio 1
	v_mfma_f32_16x16x32_bf16 v[54:57], v[186:189], v[154:157], v[54:57]
	v_mfma_f32_16x16x32_bf16 v[44:47], v[198:201], v[154:157], v[44:47]
	v_mfma_f32_16x16x32_bf16 v[36:39], v[186:189], v[162:165], v[36:39]
	v_mfma_f32_16x16x32_bf16 v[28:31], v[198:201], v[162:165], v[28:31]
	v_mfma_f32_16x16x32_bf16 v[20:23], v[186:189], v[170:173], v[20:23]
	v_mfma_f32_16x16x32_bf16 v[12:15], v[198:201], v[170:173], v[12:15]
	v_mfma_f32_16x16x32_bf16 v[4:7], v[186:189], v[178:181], v[4:7]
	v_mfma_f32_16x16x32_bf16 v[0:3], v[198:201], v[178:181], v[0:3]
	v_mfma_f32_16x16x32_bf16 v[54:57], v[190:193], v[158:161], v[54:57]
	v_mfma_f32_16x16x32_bf16 v[44:47], v[202:205], v[158:161], v[44:47]
	v_mfma_f32_16x16x32_bf16 v[36:39], v[190:193], v[166:169], v[36:39]
	v_mfma_f32_16x16x32_bf16 v[28:31], v[202:205], v[166:169], v[28:31]
	v_mfma_f32_16x16x32_bf16 v[20:23], v[190:193], v[174:177], v[20:23]
	v_mfma_f32_16x16x32_bf16 v[12:15], v[202:205], v[174:177], v[12:15]
	v_mfma_f32_16x16x32_bf16 v[4:7], v[190:193], v[182:185], v[4:7]
	v_mfma_f32_16x16x32_bf16 v[0:3], v[202:205], v[182:185], v[0:3]
	s_setprio 0
	s_add_i32 s47, 0, 0x18000
	v_add_u32_e32 v142, s47, v242
	s_barrier
	ds_read_b128 v[130:133], v142
	ds_read_b128 v[134:137], v142 offset:1024
	ds_read_b128 v[138:141], v142 offset:2048
	ds_read_b128 v[142:145], v142 offset:3072
	s_add_u32 s18, s24, 0xb0000
	s_addc_u32 s19, s25, 0
	s_mov_b32 m0, s35
	v_lshl_add_u64 v[186:187], s[18:19], 0, v[48:49]
	ds_read_b128 v[154:157], v244 offset:32768
	ds_read_b128 v[158:161], v244 offset:33792
	ds_read_b128 v[162:165], v244 offset:34816
	ds_read_b128 v[166:169], v244 offset:35840
	ds_read_b128 v[170:173], v244 offset:36864
	ds_read_b128 v[174:177], v244 offset:37888
	ds_read_b128 v[178:181], v244 offset:38912
	ds_read_b128 v[182:185], v244 offset:39936
	global_load_lds_dwordx4 v[186:187], off
	v_lshl_add_u64 v[186:187], s[18:19], 0, v[146:147]
	s_mov_b32 m0, s36
	s_nop 0
	global_load_lds_dwordx4 v[186:187], off
	s_waitcnt lgkmcnt(8)
	s_barrier
	s_waitcnt lgkmcnt(0)
	s_setprio 1
	s_waitcnt lgkmcnt(0)
	v_mfma_f32_16x16x32_bf16 v[126:129], v[130:133], v[154:157], v[126:129]
	v_mfma_f32_16x16x32_bf16 v[122:125], v[138:141], v[154:157], v[122:125]
	v_mfma_f32_16x16x32_bf16 v[114:117], v[130:133], v[162:165], v[114:117]
	v_mfma_f32_16x16x32_bf16 v[106:109], v[138:141], v[162:165], v[106:109]
	v_mfma_f32_16x16x32_bf16 v[98:101], v[130:133], v[170:173], v[98:101]
	v_mfma_f32_16x16x32_bf16 v[90:93], v[138:141], v[170:173], v[90:93]
	v_mfma_f32_16x16x32_bf16 v[82:85], v[130:133], v[178:181], v[82:85]
	v_mfma_f32_16x16x32_bf16 v[74:77], v[138:141], v[178:181], v[74:77]
	v_mfma_f32_16x16x32_bf16 v[126:129], v[134:137], v[158:161], v[126:129]
	v_mfma_f32_16x16x32_bf16 v[122:125], v[142:145], v[158:161], v[122:125]
	v_mfma_f32_16x16x32_bf16 v[114:117], v[134:137], v[166:169], v[114:117]
	v_mfma_f32_16x16x32_bf16 v[106:109], v[142:145], v[166:169], v[106:109]
	v_mfma_f32_16x16x32_bf16 v[98:101], v[134:137], v[174:177], v[98:101]
	v_mfma_f32_16x16x32_bf16 v[90:93], v[142:145], v[174:177], v[90:93]
	v_mfma_f32_16x16x32_bf16 v[82:85], v[134:137], v[182:185], v[82:85]
	v_mfma_f32_16x16x32_bf16 v[74:77], v[142:145], v[182:185], v[74:77]
	s_setprio 0
	s_barrier
	s_add_i32 s24, 0, 0x1c000
	s_add_i32 s18, s47, s30
	v_add_u32_e32 v202, s24, v242
	v_lshl_add_u64 v[206:207], v[206:207], 0, s[66:67]
	s_mov_b32 m0, s18
	ds_read_b128 v[186:189], v202
	ds_read_b128 v[190:193], v202 offset:1024
	ds_read_b128 v[198:201], v202 offset:2048
	ds_read_b128 v[202:205], v202 offset:3072
	global_load_lds_dwordx4 v[206:207], off
	v_lshl_add_u64 v[206:207], v[208:209], 0, s[66:67]
	s_add_i32 m0, s18, 0x2000
	s_nop 0
	global_load_lds_dwordx4 v[206:207], off
	s_barrier
	s_waitcnt lgkmcnt(0)
	s_setprio 1
	s_waitcnt lgkmcnt(0)
	v_mfma_f32_16x16x32_bf16 v[118:121], v[186:189], v[154:157], v[118:121]
	v_mfma_f32_16x16x32_bf16 v[110:113], v[198:201], v[154:157], v[110:113]
	v_mfma_f32_16x16x32_bf16 v[102:105], v[186:189], v[162:165], v[102:105]
	v_mfma_f32_16x16x32_bf16 v[94:97], v[198:201], v[162:165], v[94:97]
	v_mfma_f32_16x16x32_bf16 v[86:89], v[186:189], v[170:173], v[86:89]
	v_mfma_f32_16x16x32_bf16 v[78:81], v[198:201], v[170:173], v[78:81]
	v_mfma_f32_16x16x32_bf16 v[70:73], v[186:189], v[178:181], v[70:73]
	v_mfma_f32_16x16x32_bf16 v[66:69], v[198:201], v[178:181], v[66:69]
	v_mfma_f32_16x16x32_bf16 v[118:121], v[190:193], v[158:161], v[118:121]
	v_mfma_f32_16x16x32_bf16 v[110:113], v[202:205], v[158:161], v[110:113]
	v_mfma_f32_16x16x32_bf16 v[102:105], v[190:193], v[166:169], v[102:105]
	v_mfma_f32_16x16x32_bf16 v[94:97], v[202:205], v[166:169], v[94:97]
	v_mfma_f32_16x16x32_bf16 v[86:89], v[190:193], v[174:177], v[86:89]
	v_mfma_f32_16x16x32_bf16 v[78:81], v[202:205], v[174:177], v[78:81]
	v_mfma_f32_16x16x32_bf16 v[70:73], v[190:193], v[182:185], v[70:73]
	v_mfma_f32_16x16x32_bf16 v[66:69], v[202:205], v[182:185], v[66:69]
	s_setprio 0
	s_mov_b32 m0, s39
	v_lshl_add_u64 v[206:207], v[210:211], 0, s[66:67]
	s_barrier
	ds_read_b128 v[154:157], v244 offset:49152
	ds_read_b128 v[158:161], v244 offset:50176
	ds_read_b128 v[162:165], v244 offset:51200
	ds_read_b128 v[166:169], v244 offset:52224
	ds_read_b128 v[170:173], v244 offset:53248
	ds_read_b128 v[174:177], v244 offset:54272
	ds_read_b128 v[178:181], v244 offset:55296
	ds_read_b128 v[182:185], v244 offset:56320
	global_load_lds_dwordx4 v[206:207], off
	v_lshl_add_u64 v[206:207], v[212:213], 0, s[66:67]
	s_mov_b32 m0, s40
	s_nop 0
	global_load_lds_dwordx4 v[206:207], off
	s_barrier
	s_waitcnt lgkmcnt(0)
	s_setprio 1
	s_waitcnt lgkmcnt(0)
	v_mfma_f32_16x16x32_bf16 v[62:65], v[130:133], v[154:157], v[62:65]
	v_mfma_f32_16x16x32_bf16 v[58:61], v[138:141], v[154:157], v[58:61]
	v_mfma_f32_16x16x32_bf16 v[50:53], v[130:133], v[162:165], v[50:53]
	v_mfma_f32_16x16x32_bf16 v[40:43], v[138:141], v[162:165], v[40:43]
	v_mfma_f32_16x16x32_bf16 v[32:35], v[130:133], v[170:173], v[32:35]
	v_mfma_f32_16x16x32_bf16 v[24:27], v[138:141], v[170:173], v[24:27]
	v_mfma_f32_16x16x32_bf16 v[16:19], v[130:133], v[178:181], v[16:19]
	v_mfma_f32_16x16x32_bf16 v[8:11], v[138:141], v[178:181], v[8:11]
	v_mfma_f32_16x16x32_bf16 v[62:65], v[134:137], v[158:161], v[62:65]
	v_mfma_f32_16x16x32_bf16 v[58:61], v[142:145], v[158:161], v[58:61]
	v_mfma_f32_16x16x32_bf16 v[50:53], v[134:137], v[166:169], v[50:53]
	v_mfma_f32_16x16x32_bf16 v[40:43], v[142:145], v[166:169], v[40:43]
	v_mfma_f32_16x16x32_bf16 v[32:35], v[134:137], v[174:177], v[32:35]
	v_mfma_f32_16x16x32_bf16 v[24:27], v[142:145], v[174:177], v[24:27]
	v_mfma_f32_16x16x32_bf16 v[16:19], v[134:137], v[182:185], v[16:19]
	v_mfma_f32_16x16x32_bf16 v[8:11], v[142:145], v[182:185], v[8:11]
	s_setprio 0
	s_barrier
	s_add_u32 s18, s22, 0xb0080
	s_addc_u32 s19, s23, 0
	s_add_i32 s22, s24, s30
	v_lshl_add_u64 v[130:131], s[18:19], 0, v[48:49]
	s_mov_b32 m0, s22
	s_nop 0
	global_load_lds_dwordx4 v[130:131], off
	v_lshl_add_u64 v[130:131], s[18:19], 0, v[146:147]
	s_add_i32 m0, s22, 0x2000
	s_nop 0
	global_load_lds_dwordx4 v[130:131], off
	s_waitcnt vmcnt(6)
	s_barrier
	s_setprio 1
	v_mfma_f32_16x16x32_bf16 v[54:57], v[186:189], v[154:157], v[54:57]
	v_mfma_f32_16x16x32_bf16 v[44:47], v[198:201], v[154:157], v[44:47]
	v_mfma_f32_16x16x32_bf16 v[36:39], v[186:189], v[162:165], v[36:39]
	v_mfma_f32_16x16x32_bf16 v[28:31], v[198:201], v[162:165], v[28:31]
	v_mfma_f32_16x16x32_bf16 v[20:23], v[186:189], v[170:173], v[20:23]
	v_mfma_f32_16x16x32_bf16 v[12:15], v[198:201], v[170:173], v[12:15]
	v_mfma_f32_16x16x32_bf16 v[4:7], v[186:189], v[178:181], v[4:7]
	v_mfma_f32_16x16x32_bf16 v[0:3], v[198:201], v[178:181], v[0:3]
	v_mfma_f32_16x16x32_bf16 v[54:57], v[190:193], v[158:161], v[54:57]
	v_mfma_f32_16x16x32_bf16 v[44:47], v[202:205], v[158:161], v[44:47]
	v_mfma_f32_16x16x32_bf16 v[36:39], v[190:193], v[166:169], v[36:39]
	v_mfma_f32_16x16x32_bf16 v[28:31], v[202:205], v[166:169], v[28:31]
	v_mfma_f32_16x16x32_bf16 v[20:23], v[190:193], v[174:177], v[20:23]
	v_mfma_f32_16x16x32_bf16 v[12:15], v[202:205], v[174:177], v[12:15]
	v_mfma_f32_16x16x32_bf16 v[4:7], v[190:193], v[182:185], v[4:7]
	v_mfma_f32_16x16x32_bf16 v[0:3], v[202:205], v[182:185], v[0:3]
	s_setprio 0
	s_add_i32 s46, s46, 2
	s_add_u32 s44, s44, 0x100
	s_addc_u32 s45, s45, 0
	s_cmp_gt_u32 s46, 41
	s_mov_b64 s[18:19], s[20:21]
	s_barrier
	s_cbranch_scc0 .LBB0_1435
	s_mul_hi_i32 s18, s16, 0x38e38e39
	s_lshr_b32 s19, s18, 31
	s_ashr_i32 s18, s18, 1
	s_add_i32 s18, s18, s19
	s_mul_i32 s19, s18, -9
	v_lshl_or_b32 v154, s17, 8, v243
	s_sub_i32 s17, 0, s16
	s_cmp_lg_u32 s19, s17
	s_cselect_b32 s17, s18, 32
	s_mul_hi_i32 s19, s17, 0x6000
	s_mulk_i32 s17, 0x6000
	s_add_u32 s18, s37, s17
	s_addc_u32 s19, s38, s19
	s_ashr_i32 s17, s16, 31
	s_lshl_b64 s[16:17], s[16:17], 18
	v_ashrrev_i32_e32 v155, 31, v154
	v_lshl_add_u64 v[156:157], s[16:17], 0, v[148:149]
	v_lshl_add_u64 v[130:131], v[154:155], 2, s[18:19]
	v_lshl_add_u64 v[154:155], v[156:157], 0, v[154:155]
	v_lshlrev_b64 v[184:185], 1, v[154:155]
	v_lshl_add_u64 v[154:155], s[10:11], 0, v[184:185]
	global_load_dwordx4 v[142:145], v[130:131], off
	global_load_dwordx4 v[138:141], v[130:131], off offset:64
	global_load_dwordx4 v[134:137], v[130:131], off offset:512
	s_nop 0
	global_load_dwordx4 v[130:133], v[130:131], off offset:576
	s_nop 0
	s_mov_b32 s16, 0x40000
	s_nop 0
	s_mov_b32 s17, 0x48000
	s_nop 0
	s_mov_b32 s18, 0x50000
	s_nop 0
	s_mov_b32 s19, 0x58000
	s_nop 0
	v_lshl_add_u64 v[184:185], s[6:7], 0, v[184:185]
	s_nop 0
	s_mov_b64 s[20:21], s[14:15]
	s_nop 0
	v_and_b32_e32 v210, 16, v224
	v_lshrrev_b32_e32 v211, 1, v210
	v_add_u32_e32 v210, v210, v211
	v_mov_b32_e32 v211, 0
	v_mov_b32_e32 v213, 0
	v_lshl_add_u64 v[214:215], v[154:155], 0, v[210:211]
	v_lshl_add_u64 v[216:217], v[184:185], 0, v[210:211]
	v_mov_b32_e32 v212, 0x0
	v_lshl_add_u64 v[218:219], v[214:215], 0, v[212:213]
	global_load_dwordx4 v[164:167], v[218:219], off
	global_load_dwordx4 v[168:171], v[218:219], off offset:256
	v_mov_b32_e32 v212, 0x8000
	v_lshl_add_u64 v[218:219], v[214:215], 0, v[212:213]
	global_load_dwordx4 v[172:175], v[218:219], off
	global_load_dwordx4 v[176:179], v[218:219], off offset:256
	v_mov_b32_e32 v212, 0x10000
	v_lshl_add_u64 v[218:219], v[214:215], 0, v[212:213]
	global_load_dwordx4 v[180:183], v[218:219], off
	global_load_dwordx4 v[198:201], v[218:219], off offset:256
	v_mov_b32_e32 v212, 0x18000
	v_lshl_add_u64 v[218:219], v[214:215], 0, v[212:213]
	global_load_dwordx4 v[202:205], v[218:219], off
	global_load_dwordx4 v[206:209], v[218:219], off offset:256
	s_waitcnt vmcnt(7)
	v_permlane16_swap_b32 v164, v166
	v_permlane16_swap_b32 v165, v167
	s_nop 1
	v_lshlrev_b32_e32 v186, 16, v164
	v_and_b32_e32 v187, 0xffff0000, v164
	v_lshlrev_b32_e32 v188, 16, v165
	v_and_b32_e32 v189, 0xffff0000, v165
	v_pk_fma_f32 v[126:127], v[126:127], v[142:143], v[186:187]
	v_pk_fma_f32 v[128:129], v[128:129], v[144:145], v[188:189]
	v_lshlrev_b32_e32 v190, 16, v166
	v_and_b32_e32 v191, 0xffff0000, v166
	v_lshlrev_b32_e32 v192, 16, v167
	v_and_b32_e32 v193, 0xffff0000, v167
	v_pk_fma_f32 v[122:123], v[122:123], v[138:139], v[190:191]
	v_pk_fma_f32 v[124:125], v[124:125], v[140:141], v[192:193]
	v_cvt_pk_bf16_f32 v126, v126, v127
	v_cvt_pk_bf16_f32 v127, v128, v129
	v_cvt_pk_bf16_f32 v128, v122, v123
	v_cvt_pk_bf16_f32 v129, v124, v125
	s_nop 1
	v_permlane16_swap_b32 v126, v128
	v_permlane16_swap_b32 v127, v129
	v_mov_b32_e32 v212, 0x0
	v_lshl_add_u64 v[220:221], v[216:217], 0, v[212:213]
	global_store_dwordx4 v[220:221], v[126:129], off
	v_mov_b32_e32 v212, 0x40000
	v_lshl_add_u64 v[218:219], v[214:215], 0, v[212:213]
	global_load_dwordx4 v[164:167], v[218:219], off
	s_waitcnt vmcnt(8)
	v_permlane16_swap_b32 v168, v170
	v_permlane16_swap_b32 v169, v171
	s_nop 1
	v_lshlrev_b32_e32 v186, 16, v168
	v_and_b32_e32 v187, 0xffff0000, v168
	v_lshlrev_b32_e32 v188, 16, v169
	v_and_b32_e32 v189, 0xffff0000, v169
	v_pk_fma_f32 v[118:119], v[118:119], v[134:135], v[186:187]
	v_pk_fma_f32 v[120:121], v[120:121], v[136:137], v[188:189]
	v_lshlrev_b32_e32 v190, 16, v170
	v_and_b32_e32 v191, 0xffff0000, v170
	v_lshlrev_b32_e32 v192, 16, v171
	v_and_b32_e32 v193, 0xffff0000, v171
	v_pk_fma_f32 v[110:111], v[110:111], v[130:131], v[190:191]
	v_pk_fma_f32 v[112:113], v[112:113], v[132:133], v[192:193]
	v_cvt_pk_bf16_f32 v118, v118, v119
	v_cvt_pk_bf16_f32 v119, v120, v121
	v_cvt_pk_bf16_f32 v120, v110, v111
	v_cvt_pk_bf16_f32 v121, v112, v113
	s_nop 1
	v_permlane16_swap_b32 v118, v120
	v_permlane16_swap_b32 v119, v121
	v_mov_b32_e32 v212, 0x0
	v_lshl_add_u64 v[220:221], v[216:217], 0, v[212:213]
	global_store_dwordx4 v[220:221], v[118:121], off offset:256
	global_load_dwordx4 v[168:171], v[218:219], off offset:256
	s_waitcnt vmcnt(9)
	v_permlane16_swap_b32 v172, v174
	v_permlane16_swap_b32 v173, v175
	s_nop 1
	v_lshlrev_b32_e32 v186, 16, v172
	v_and_b32_e32 v187, 0xffff0000, v172
	v_lshlrev_b32_e32 v188, 16, v173
	v_and_b32_e32 v189, 0xffff0000, v173
	v_pk_fma_f32 v[114:115], v[114:115], v[142:143], v[186:187]
	v_pk_fma_f32 v[116:117], v[116:117], v[144:145], v[188:189]
	v_lshlrev_b32_e32 v190, 16, v174
	v_and_b32_e32 v191, 0xffff0000, v174
	v_lshlrev_b32_e32 v192, 16, v175
	v_and_b32_e32 v193, 0xffff0000, v175
	v_pk_fma_f32 v[106:107], v[106:107], v[138:139], v[190:191]
	v_pk_fma_f32 v[108:109], v[108:109], v[140:141], v[192:193]
	v_cvt_pk_bf16_f32 v114, v114, v115
	v_cvt_pk_bf16_f32 v115, v116, v117
	v_cvt_pk_bf16_f32 v116, v106, v107
	v_cvt_pk_bf16_f32 v117, v108, v109
	s_nop 1
	v_permlane16_swap_b32 v114, v116
	v_permlane16_swap_b32 v115, v117
	v_mov_b32_e32 v212, 0x8000
	v_lshl_add_u64 v[220:221], v[216:217], 0, v[212:213]
	global_store_dwordx4 v[220:221], v[114:117], off
	v_mov_b32_e32 v212, 0x48000
	v_lshl_add_u64 v[218:219], v[214:215], 0, v[212:213]
	global_load_dwordx4 v[172:175], v[218:219], off
	s_waitcnt vmcnt(10)
	v_permlane16_swap_b32 v176, v178
	v_permlane16_swap_b32 v177, v179
	s_nop 1
	v_lshlrev_b32_e32 v186, 16, v176
	v_and_b32_e32 v187, 0xffff0000, v176
	v_lshlrev_b32_e32 v188, 16, v177
	v_and_b32_e32 v189, 0xffff0000, v177
	v_pk_fma_f32 v[102:103], v[102:103], v[134:135], v[186:187]
	v_pk_fma_f32 v[104:105], v[104:105], v[136:137], v[188:189]
	v_lshlrev_b32_e32 v190, 16, v178
	v_and_b32_e32 v191, 0xffff0000, v178
	v_lshlrev_b32_e32 v192, 16, v179
	v_and_b32_e32 v193, 0xffff0000, v179
	v_pk_fma_f32 v[94:95], v[94:95], v[130:131], v[190:191]
	v_pk_fma_f32 v[96:97], v[96:97], v[132:133], v[192:193]
	v_cvt_pk_bf16_f32 v102, v102, v103
	v_cvt_pk_bf16_f32 v103, v104, v105
	v_cvt_pk_bf16_f32 v104, v94, v95
	v_cvt_pk_bf16_f32 v105, v96, v97
	s_nop 1
	v_permlane16_swap_b32 v102, v104
	v_permlane16_swap_b32 v103, v105
	v_mov_b32_e32 v212, 0x8000
	v_lshl_add_u64 v[220:221], v[216:217], 0, v[212:213]
	global_store_dwordx4 v[220:221], v[102:105], off offset:256
	global_load_dwordx4 v[176:179], v[218:219], off offset:256
	s_waitcnt vmcnt(11)
	v_permlane16_swap_b32 v180, v182
	v_permlane16_swap_b32 v181, v183
	s_nop 1
	v_lshlrev_b32_e32 v186, 16, v180
	v_and_b32_e32 v187, 0xffff0000, v180
	v_lshlrev_b32_e32 v188, 16, v181
	v_and_b32_e32 v189, 0xffff0000, v181
	v_pk_fma_f32 v[98:99], v[98:99], v[142:143], v[186:187]
	v_pk_fma_f32 v[100:101], v[100:101], v[144:145], v[188:189]
	v_lshlrev_b32_e32 v190, 16, v182
	v_and_b32_e32 v191, 0xffff0000, v182
	v_lshlrev_b32_e32 v192, 16, v183
	v_and_b32_e32 v193, 0xffff0000, v183
	v_pk_fma_f32 v[90:91], v[90:91], v[138:139], v[190:191]
	v_pk_fma_f32 v[92:93], v[92:93], v[140:141], v[192:193]
	v_cvt_pk_bf16_f32 v98, v98, v99
	v_cvt_pk_bf16_f32 v99, v100, v101
	v_cvt_pk_bf16_f32 v100, v90, v91
	v_cvt_pk_bf16_f32 v101, v92, v93
	s_nop 1
	v_permlane16_swap_b32 v98, v100
	v_permlane16_swap_b32 v99, v101
	v_mov_b32_e32 v212, 0x10000
	v_lshl_add_u64 v[220:221], v[216:217], 0, v[212:213]
	global_store_dwordx4 v[220:221], v[98:101], off
	v_mov_b32_e32 v212, 0x50000
	v_lshl_add_u64 v[218:219], v[214:215], 0, v[212:213]
	global_load_dwordx4 v[180:183], v[218:219], off
	s_waitcnt vmcnt(12)
	v_permlane16_swap_b32 v198, v200
	v_permlane16_swap_b32 v199, v201
	s_nop 1
	v_lshlrev_b32_e32 v186, 16, v198
	v_and_b32_e32 v187, 0xffff0000, v198
	v_lshlrev_b32_e32 v188, 16, v199
	v_and_b32_e32 v189, 0xffff0000, v199
	v_pk_fma_f32 v[86:87], v[86:87], v[134:135], v[186:187]
	v_pk_fma_f32 v[88:89], v[88:89], v[136:137], v[188:189]
	v_lshlrev_b32_e32 v190, 16, v200
	v_and_b32_e32 v191, 0xffff0000, v200
	v_lshlrev_b32_e32 v192, 16, v201
	v_and_b32_e32 v193, 0xffff0000, v201
	v_pk_fma_f32 v[78:79], v[78:79], v[130:131], v[190:191]
	v_pk_fma_f32 v[80:81], v[80:81], v[132:133], v[192:193]
	v_cvt_pk_bf16_f32 v86, v86, v87
	v_cvt_pk_bf16_f32 v87, v88, v89
	v_cvt_pk_bf16_f32 v88, v78, v79
	v_cvt_pk_bf16_f32 v89, v80, v81
	s_nop 1
	v_permlane16_swap_b32 v86, v88
	v_permlane16_swap_b32 v87, v89
	v_mov_b32_e32 v212, 0x10000
	v_lshl_add_u64 v[220:221], v[216:217], 0, v[212:213]
	global_store_dwordx4 v[220:221], v[86:89], off offset:256
	global_load_dwordx4 v[198:201], v[218:219], off offset:256
	s_waitcnt vmcnt(13)
	v_permlane16_swap_b32 v202, v204
	v_permlane16_swap_b32 v203, v205
	s_nop 1
	v_lshlrev_b32_e32 v186, 16, v202
	v_and_b32_e32 v187, 0xffff0000, v202
	v_lshlrev_b32_e32 v188, 16, v203
	v_and_b32_e32 v189, 0xffff0000, v203
	v_pk_fma_f32 v[82:83], v[82:83], v[142:143], v[186:187]
	v_pk_fma_f32 v[84:85], v[84:85], v[144:145], v[188:189]
	v_lshlrev_b32_e32 v190, 16, v204
	v_and_b32_e32 v191, 0xffff0000, v204
	v_lshlrev_b32_e32 v192, 16, v205
	v_and_b32_e32 v193, 0xffff0000, v205
	v_pk_fma_f32 v[74:75], v[74:75], v[138:139], v[190:191]
	v_pk_fma_f32 v[76:77], v[76:77], v[140:141], v[192:193]
	v_cvt_pk_bf16_f32 v82, v82, v83
	v_cvt_pk_bf16_f32 v83, v84, v85
	v_cvt_pk_bf16_f32 v84, v74, v75
	v_cvt_pk_bf16_f32 v85, v76, v77
	s_nop 1
	v_permlane16_swap_b32 v82, v84
	v_permlane16_swap_b32 v83, v85
	v_mov_b32_e32 v212, 0x18000
	v_lshl_add_u64 v[220:221], v[216:217], 0, v[212:213]
	global_store_dwordx4 v[220:221], v[82:85], off
	v_mov_b32_e32 v212, 0x58000
	v_lshl_add_u64 v[218:219], v[214:215], 0, v[212:213]
	global_load_dwordx4 v[202:205], v[218:219], off
	s_waitcnt vmcnt(14)
	v_permlane16_swap_b32 v206, v208
	v_permlane16_swap_b32 v207, v209
	s_nop 1
	v_lshlrev_b32_e32 v186, 16, v206
	v_and_b32_e32 v187, 0xffff0000, v206
	v_lshlrev_b32_e32 v188, 16, v207
	v_and_b32_e32 v189, 0xffff0000, v207
	v_pk_fma_f32 v[70:71], v[70:71], v[134:135], v[186:187]
	v_pk_fma_f32 v[72:73], v[72:73], v[136:137], v[188:189]
	v_lshlrev_b32_e32 v190, 16, v208
	v_and_b32_e32 v191, 0xffff0000, v208
	v_lshlrev_b32_e32 v192, 16, v209
	v_and_b32_e32 v193, 0xffff0000, v209
	v_pk_fma_f32 v[66:67], v[66:67], v[130:131], v[190:191]
	v_pk_fma_f32 v[68:69], v[68:69], v[132:133], v[192:193]
	v_cvt_pk_bf16_f32 v70, v70, v71
	v_cvt_pk_bf16_f32 v71, v72, v73
	v_cvt_pk_bf16_f32 v72, v66, v67
	v_cvt_pk_bf16_f32 v73, v68, v69
	s_nop 1
	v_permlane16_swap_b32 v70, v72
	v_permlane16_swap_b32 v71, v73
	v_mov_b32_e32 v212, 0x18000
	v_lshl_add_u64 v[220:221], v[216:217], 0, v[212:213]
	global_store_dwordx4 v[220:221], v[70:73], off offset:256
	global_load_dwordx4 v[206:209], v[218:219], off offset:256
	s_waitcnt vmcnt(14)
	v_permlane16_swap_b32 v164, v166
	v_permlane16_swap_b32 v165, v167
	s_nop 1
	v_lshlrev_b32_e32 v186, 16, v164
	v_and_b32_e32 v187, 0xffff0000, v164
	v_lshlrev_b32_e32 v188, 16, v165
	v_and_b32_e32 v189, 0xffff0000, v165
	v_pk_fma_f32 v[62:63], v[62:63], v[142:143], v[186:187]
	v_pk_fma_f32 v[64:65], v[64:65], v[144:145], v[188:189]
	v_lshlrev_b32_e32 v190, 16, v166
	v_and_b32_e32 v191, 0xffff0000, v166
	v_lshlrev_b32_e32 v192, 16, v167
	v_and_b32_e32 v193, 0xffff0000, v167
	v_pk_fma_f32 v[58:59], v[58:59], v[138:139], v[190:191]
	v_pk_fma_f32 v[60:61], v[60:61], v[140:141], v[192:193]
	v_cvt_pk_bf16_f32 v62, v62, v63
	v_cvt_pk_bf16_f32 v63, v64, v65
	v_cvt_pk_bf16_f32 v64, v58, v59
	v_cvt_pk_bf16_f32 v65, v60, v61
	s_nop 1
	v_permlane16_swap_b32 v62, v64
	v_permlane16_swap_b32 v63, v65
	v_mov_b32_e32 v212, 0x40000
	v_lshl_add_u64 v[220:221], v[216:217], 0, v[212:213]
	global_store_dwordx4 v[220:221], v[62:65], off
	s_waitcnt vmcnt(13)
	v_permlane16_swap_b32 v168, v170
	v_permlane16_swap_b32 v169, v171
	s_nop 1
	v_lshlrev_b32_e32 v186, 16, v168
	v_and_b32_e32 v187, 0xffff0000, v168
	v_lshlrev_b32_e32 v188, 16, v169
	v_and_b32_e32 v189, 0xffff0000, v169
	v_pk_fma_f32 v[54:55], v[54:55], v[134:135], v[186:187]
	v_pk_fma_f32 v[56:57], v[56:57], v[136:137], v[188:189]
	v_lshlrev_b32_e32 v190, 16, v170
	v_and_b32_e32 v191, 0xffff0000, v170
	v_lshlrev_b32_e32 v192, 16, v171
	v_and_b32_e32 v193, 0xffff0000, v171
	v_pk_fma_f32 v[44:45], v[44:45], v[130:131], v[190:191]
	v_pk_fma_f32 v[46:47], v[46:47], v[132:133], v[192:193]
	v_cvt_pk_bf16_f32 v54, v54, v55
	v_cvt_pk_bf16_f32 v55, v56, v57
	v_cvt_pk_bf16_f32 v56, v44, v45
	v_cvt_pk_bf16_f32 v57, v46, v47
	s_nop 1
	v_permlane16_swap_b32 v54, v56
	v_permlane16_swap_b32 v55, v57
	v_mov_b32_e32 v212, 0x40000
	v_lshl_add_u64 v[220:221], v[216:217], 0, v[212:213]
	global_store_dwordx4 v[220:221], v[54:57], off offset:256
	s_waitcnt vmcnt(12)
	v_permlane16_swap_b32 v172, v174
	v_permlane16_swap_b32 v173, v175
	s_nop 1
	v_lshlrev_b32_e32 v186, 16, v172
	v_and_b32_e32 v187, 0xffff0000, v172
	v_lshlrev_b32_e32 v188, 16, v173
	v_and_b32_e32 v189, 0xffff0000, v173
	v_pk_fma_f32 v[50:51], v[50:51], v[142:143], v[186:187]
	v_pk_fma_f32 v[52:53], v[52:53], v[144:145], v[188:189]
	v_lshlrev_b32_e32 v190, 16, v174
	v_and_b32_e32 v191, 0xffff0000, v174
	v_lshlrev_b32_e32 v192, 16, v175
	v_and_b32_e32 v193, 0xffff0000, v175
	v_pk_fma_f32 v[40:41], v[40:41], v[138:139], v[190:191]
	v_pk_fma_f32 v[42:43], v[42:43], v[140:141], v[192:193]
	v_cvt_pk_bf16_f32 v50, v50, v51
	v_cvt_pk_bf16_f32 v51, v52, v53
	v_cvt_pk_bf16_f32 v52, v40, v41
	v_cvt_pk_bf16_f32 v53, v42, v43
	s_nop 1
	v_permlane16_swap_b32 v50, v52
	v_permlane16_swap_b32 v51, v53
	v_mov_b32_e32 v212, 0x48000
	v_lshl_add_u64 v[220:221], v[216:217], 0, v[212:213]
	global_store_dwordx4 v[220:221], v[50:53], off
	s_waitcnt vmcnt(11)
	v_permlane16_swap_b32 v176, v178
	v_permlane16_swap_b32 v177, v179
	s_nop 1
	v_lshlrev_b32_e32 v186, 16, v176
	v_and_b32_e32 v187, 0xffff0000, v176
	v_lshlrev_b32_e32 v188, 16, v177
	v_and_b32_e32 v189, 0xffff0000, v177
	v_pk_fma_f32 v[36:37], v[36:37], v[134:135], v[186:187]
	v_pk_fma_f32 v[38:39], v[38:39], v[136:137], v[188:189]
	v_lshlrev_b32_e32 v190, 16, v178
	v_and_b32_e32 v191, 0xffff0000, v178
	v_lshlrev_b32_e32 v192, 16, v179
	v_and_b32_e32 v193, 0xffff0000, v179
	v_pk_fma_f32 v[28:29], v[28:29], v[130:131], v[190:191]
	v_pk_fma_f32 v[30:31], v[30:31], v[132:133], v[192:193]
	v_cvt_pk_bf16_f32 v36, v36, v37
	v_cvt_pk_bf16_f32 v37, v38, v39
	v_cvt_pk_bf16_f32 v38, v28, v29
	v_cvt_pk_bf16_f32 v39, v30, v31
	s_nop 1
	v_permlane16_swap_b32 v36, v38
	v_permlane16_swap_b32 v37, v39
	v_mov_b32_e32 v212, 0x48000
	v_lshl_add_u64 v[220:221], v[216:217], 0, v[212:213]
	global_store_dwordx4 v[220:221], v[36:39], off offset:256
	s_waitcnt vmcnt(10)
	v_permlane16_swap_b32 v180, v182
	v_permlane16_swap_b32 v181, v183
	s_nop 1
	v_lshlrev_b32_e32 v186, 16, v180
	v_and_b32_e32 v187, 0xffff0000, v180
	v_lshlrev_b32_e32 v188, 16, v181
	v_and_b32_e32 v189, 0xffff0000, v181
	v_pk_fma_f32 v[32:33], v[32:33], v[142:143], v[186:187]
	v_pk_fma_f32 v[34:35], v[34:35], v[144:145], v[188:189]
	v_lshlrev_b32_e32 v190, 16, v182
	v_and_b32_e32 v191, 0xffff0000, v182
	v_lshlrev_b32_e32 v192, 16, v183
	v_and_b32_e32 v193, 0xffff0000, v183
	v_pk_fma_f32 v[24:25], v[24:25], v[138:139], v[190:191]
	v_pk_fma_f32 v[26:27], v[26:27], v[140:141], v[192:193]
	v_cvt_pk_bf16_f32 v32, v32, v33
	v_cvt_pk_bf16_f32 v33, v34, v35
	v_cvt_pk_bf16_f32 v34, v24, v25
	v_cvt_pk_bf16_f32 v35, v26, v27
	s_nop 1
	v_permlane16_swap_b32 v32, v34
	v_permlane16_swap_b32 v33, v35
	v_mov_b32_e32 v212, 0x50000
	v_lshl_add_u64 v[220:221], v[216:217], 0, v[212:213]
	global_store_dwordx4 v[220:221], v[32:35], off
	s_waitcnt vmcnt(9)
	v_permlane16_swap_b32 v198, v200
	v_permlane16_swap_b32 v199, v201
	s_nop 1
	v_lshlrev_b32_e32 v186, 16, v198
	v_and_b32_e32 v187, 0xffff0000, v198
	v_lshlrev_b32_e32 v188, 16, v199
	v_and_b32_e32 v189, 0xffff0000, v199
	v_pk_fma_f32 v[20:21], v[20:21], v[134:135], v[186:187]
	v_pk_fma_f32 v[22:23], v[22:23], v[136:137], v[188:189]
	v_lshlrev_b32_e32 v190, 16, v200
	v_and_b32_e32 v191, 0xffff0000, v200
	v_lshlrev_b32_e32 v192, 16, v201
	v_and_b32_e32 v193, 0xffff0000, v201
	v_pk_fma_f32 v[12:13], v[12:13], v[130:131], v[190:191]
	v_pk_fma_f32 v[14:15], v[14:15], v[132:133], v[192:193]
	v_cvt_pk_bf16_f32 v20, v20, v21
	v_cvt_pk_bf16_f32 v21, v22, v23
	v_cvt_pk_bf16_f32 v22, v12, v13
	v_cvt_pk_bf16_f32 v23, v14, v15
	s_nop 1
	v_permlane16_swap_b32 v20, v22
	v_permlane16_swap_b32 v21, v23
	v_mov_b32_e32 v212, 0x50000
	v_lshl_add_u64 v[220:221], v[216:217], 0, v[212:213]
	global_store_dwordx4 v[220:221], v[20:23], off offset:256
	s_waitcnt vmcnt(8)
	v_permlane16_swap_b32 v202, v204
	v_permlane16_swap_b32 v203, v205
	s_nop 1
	v_lshlrev_b32_e32 v186, 16, v202
	v_and_b32_e32 v187, 0xffff0000, v202
	v_lshlrev_b32_e32 v188, 16, v203
	v_and_b32_e32 v189, 0xffff0000, v203
	v_pk_fma_f32 v[16:17], v[16:17], v[142:143], v[186:187]
	v_pk_fma_f32 v[18:19], v[18:19], v[144:145], v[188:189]
	v_lshlrev_b32_e32 v190, 16, v204
	v_and_b32_e32 v191, 0xffff0000, v204
	v_lshlrev_b32_e32 v192, 16, v205
	v_and_b32_e32 v193, 0xffff0000, v205
	v_pk_fma_f32 v[8:9], v[8:9], v[138:139], v[190:191]
	v_pk_fma_f32 v[10:11], v[10:11], v[140:141], v[192:193]
	v_cvt_pk_bf16_f32 v16, v16, v17
	v_cvt_pk_bf16_f32 v17, v18, v19
	v_cvt_pk_bf16_f32 v18, v8, v9
	v_cvt_pk_bf16_f32 v19, v10, v11
	s_nop 1
	v_permlane16_swap_b32 v16, v18
	v_permlane16_swap_b32 v17, v19
	v_mov_b32_e32 v212, 0x58000
	v_lshl_add_u64 v[220:221], v[216:217], 0, v[212:213]
	global_store_dwordx4 v[220:221], v[16:19], off
	s_waitcnt vmcnt(7)
	v_permlane16_swap_b32 v206, v208
	v_permlane16_swap_b32 v207, v209
	s_nop 1
	v_lshlrev_b32_e32 v186, 16, v206
	v_and_b32_e32 v187, 0xffff0000, v206
	v_lshlrev_b32_e32 v188, 16, v207
	v_and_b32_e32 v189, 0xffff0000, v207
	v_pk_fma_f32 v[4:5], v[4:5], v[134:135], v[186:187]
	v_pk_fma_f32 v[6:7], v[6:7], v[136:137], v[188:189]
	v_lshlrev_b32_e32 v190, 16, v208
	v_and_b32_e32 v191, 0xffff0000, v208
	v_lshlrev_b32_e32 v192, 16, v209
	v_and_b32_e32 v193, 0xffff0000, v209
	v_pk_fma_f32 v[0:1], v[0:1], v[130:131], v[190:191]
	v_pk_fma_f32 v[2:3], v[2:3], v[132:133], v[192:193]
	v_cvt_pk_bf16_f32 v4, v4, v5
	v_cvt_pk_bf16_f32 v5, v6, v7
	v_cvt_pk_bf16_f32 v6, v0, v1
	v_cvt_pk_bf16_f32 v7, v2, v3
	s_nop 1
	v_permlane16_swap_b32 v4, v6
	v_permlane16_swap_b32 v5, v7
	v_mov_b32_e32 v212, 0x58000
	v_lshl_add_u64 v[220:221], v[216:217], 0, v[212:213]
	global_store_dwordx4 v[220:221], v[4:7], off offset:256
	s_mov_b32 s16, s43
	s_mov_b32 s17, s42
	s_and_b64 vcc, exec, s[0:1]
	s_mov_b64 s[18:19], s[12:13]
	s_cbranch_vccz .LBB0_1432
	s_waitcnt vmcnt(0)
	s_cmpk_gt_u32 s29, 0xff
	s_cbranch_scc1 .LBB0_1439
	s_barrier
